# GEMM K-loops (G1, G2, UP, DN): first K iteration peeled with inline-constant 0 as MFMA C operand, removing the 128 v_mov accumulator zero-init per unit
# speedup vs baseline: 1.0137x; 1.0051x over previous
;     __device__ __forceinline__ long arow(int pm) const { return (long)pm * BM; }
;     __device__ __forceinline__ long arow(int pm) const { if (pm < 132) { const int b = pm / 33, i = pm - b * 33; return (long)b * 8192 + 254 * i - 1; } return 32768 + (long)(pm - 132) * 256; }
;     __device__ __forceinline__ bool next(int i, Unit& u) const { if (i > 0) return false; u.pm = pm; u.pn = pn; return true; }
;     __device__ __forceinline__ long arow(int p) const { return (long)p * BM; }
; #define PG8_LDA(dst, b, h) do { _Pragma("unroll") for (int m = 0; m < 4; ++m) _Pragma("unroll") for (int k = 0; k < 2; ++k) dst[m][k] = *(const PG8_LAS bf16x8*)(lds + PG8_SA(b, h) + aoff + m * 2048 + k * 1024); } while (0)
; template <class Epi, class Sched, bool ALIGN_EPI = false, bool SP2 = false>
; __device__ __forceinline__ void gemm_phase(PG8_LAS unsigned char* lds, const Gemm g, const Sched& S, const Epi& E) {
;     ...
;         const bool has_next = S.next(ui + 1, nxt);
;         const char* nA = has_next ? (const char*)g.A + S.arow(nxt.pm) * rowb : cA; const char* nB = has_next ? (const char*)g.Bt + (size_t)nxt.pn * tstep : cB;
;         for (int t = 0; t < nt; t += 2) {
;             const bool last = (t == nt - 2);
;             const char* a1 = cA + (size_t)(t + 1) * kstep;
;             const char* a2 = last ? nA : cA + (size_t)(t + 2) * kstep; const char* b2 = last ? nB : cB + (size_t)(t + 2) * kstep;
;             const char* a3 = a2 + kstep; const char* b3 = b2 + kstep;
;             if (last && has_next) S.a_ready(nxt);
;             if constexpr (SP2) {
;             PG8_LDB(B0, 0, 0); PG8_LDB(B1, 0, 1); PG8_SCHED; PG8_LDA(At, 0, 0); PG8_STAGE(PG8_SA(1, 1), a1 + hstep, voffA);
;             PG8_WAIT_V(8); PG8_WAIT_L(0); PG8_BAR; PG8_MMA(0, 0, At, B0); PG8_MMA(0, 1, At, B1); PG8_BAR; PG8_SCHED;
;             PG8_LDA(At, 0, 1); PG8_STAGE(PG8_SB(0, 0), b2, voffB); PG8_STAGE(PG8_SB(0, 1), b2 + hstep, voffB); PG8_STAGE(PG8_SA(0, 0), a2, voffA);
;             PG8_WAIT_V(8); PG8_WAIT_L(0); PG8_BAR; PG8_MMA(1, 0, At, B0); PG8_MMA(1, 1, At, B1); PG8_BAR; PG8_SCHED;
;     ...
;         for (int a = 0; a < 2; ++a)
; #pragma unroll
;             for (int b = 0; b < 2; ++b)
; #pragma unroll
;                 for (int m = 0; m < 4; ++m)
; #pragma unroll
;                     for (int n = 0; n < 2; ++n) acc[a][b][m][n] = (f32x4){0.f, 0.f, 0.f, 0.f};
.LBB0_184:
	s_ashr_i32 s9, s8, 31
	s_lshl_b64 s[10:11], s[8:9], 19
	s_add_u32 s10, s90, s10
	s_addc_u32 s11, s91, s11
	s_and_b64 s[12:13], s[0:1], exec
	s_cselect_b32 s9, s11, s17
	s_cselect_b32 s36, s10, s16
	s_ashr_i32 s7, s6, 31
	s_lshl_b64 s[12:13], s[6:7], 19
	s_add_u32 s12, s22, s12
	s_addc_u32 s13, s23, s13
	s_and_b64 s[20:21], s[0:1], exec
	s_cselect_b32 s7, s13, s19
	s_cselect_b32 s37, s12, s18
	s_add_u32 s16, s16, 0x40080
	s_addc_u32 s17, s17, 0
	s_add_u32 s38, s18, 0x100
	s_addc_u32 s39, s19, 0
	s_mov_b32 s40, -2
	s_waitcnt vmcnt(0)
	s_add_u32 s18, s16, 0xfffc0080
	s_addc_u32 s19, s17, -1
	s_add_i32 s41, 0, 0x10000
	s_cmp_eq_u32 s40, 12
	s_cselect_b32 s21, s9, s19
	s_cselect_b32 s20, s36, s18
	v_add_u32_e32 v38, s41, v151
	s_cselect_b32 s19, s7, s39
	s_cselect_b32 s18, s37, s38
	s_add_i32 s44, 0, 0x14000
	ds_read_b128 v[146:149], v38
	ds_read_b128 v[154:157], v38 offset:1024
	ds_read_b128 v[158:161], v38 offset:2048
	ds_read_b128 v[162:165], v38 offset:3072
	v_add_u32_e32 v38, s44, v151
	ds_read_b128 v[166:169], v38
	ds_read_b128 v[170:173], v38 offset:1024
	ds_read_b128 v[174:177], v38 offset:2048
	ds_read_b128 v[178:181], v38 offset:3072
	v_lshl_add_u64 v[202:203], s[16:17], 0, v[142:143]
	s_add_i32 m0, s25, 0xc000
	ds_read_b128 v[186:189], v153
	ds_read_b128 v[190:193], v153 offset:1024
	ds_read_b128 v[194:197], v153 offset:2048
	ds_read_b128 v[198:201], v153 offset:3072
	ds_read_b128 v[226:229], v153 offset:4096
	ds_read_b128 v[230:233], v153 offset:5120
	ds_read_b128 v[234:237], v153 offset:6144
	ds_read_b128 v[238:241], v153 offset:7168
	global_load_lds_dwordx4 v[202:203], off
	v_lshl_add_u64 v[202:203], s[16:17], 0, v[144:145]
	s_add_i32 m0, s25, 0xe000
	s_nop 0
	global_load_lds_dwordx4 v[202:203], off
	s_waitcnt vmcnt(8)
	s_waitcnt lgkmcnt(0)
	s_barrier
	s_setprio 1
	s_waitcnt lgkmcnt(0)
	v_mfma_f32_16x16x32_bf16 v[134:137], v[146:149], v[186:189], 0
	v_mfma_f32_16x16x32_bf16 v[130:133], v[158:161], v[186:189], 0
	v_mfma_f32_16x16x32_bf16 v[126:129], v[146:149], v[194:197], 0
	v_mfma_f32_16x16x32_bf16 v[118:121], v[158:161], v[194:197], 0
	v_mfma_f32_16x16x32_bf16 v[110:113], v[146:149], v[226:229], 0
	v_mfma_f32_16x16x32_bf16 v[102:105], v[158:161], v[226:229], 0
	v_mfma_f32_16x16x32_bf16 v[94:97], v[146:149], v[234:237], 0
	v_mfma_f32_16x16x32_bf16 v[86:89], v[158:161], v[234:237], 0
	v_mfma_f32_16x16x32_bf16 v[134:137], v[154:157], v[190:193], v[134:137]
	v_mfma_f32_16x16x32_bf16 v[130:133], v[162:165], v[190:193], v[130:133]
	v_mfma_f32_16x16x32_bf16 v[126:129], v[154:157], v[198:201], v[126:129]
	v_mfma_f32_16x16x32_bf16 v[118:121], v[162:165], v[198:201], v[118:121]
	v_mfma_f32_16x16x32_bf16 v[110:113], v[154:157], v[230:233], v[110:113]
	v_mfma_f32_16x16x32_bf16 v[102:105], v[162:165], v[230:233], v[102:105]
	v_mfma_f32_16x16x32_bf16 v[94:97], v[154:157], v[238:241], v[94:97]
	v_mfma_f32_16x16x32_bf16 v[86:89], v[162:165], v[238:241], v[86:89]
	s_setprio 0
	s_setprio 1
	v_mfma_f32_16x16x32_bf16 v[122:125], v[166:169], v[186:189], 0
	v_mfma_f32_16x16x32_bf16 v[114:117], v[174:177], v[186:189], 0
	v_mfma_f32_16x16x32_bf16 v[106:109], v[166:169], v[194:197], 0
	v_mfma_f32_16x16x32_bf16 v[98:101], v[174:177], v[194:197], 0
	v_mfma_f32_16x16x32_bf16 v[90:93], v[166:169], v[226:229], 0
	v_mfma_f32_16x16x32_bf16 v[82:85], v[174:177], v[226:229], 0
	v_mfma_f32_16x16x32_bf16 v[78:81], v[166:169], v[234:237], 0
	v_mfma_f32_16x16x32_bf16 v[74:77], v[174:177], v[234:237], 0
	v_mfma_f32_16x16x32_bf16 v[122:125], v[170:173], v[190:193], v[122:125]
	v_mfma_f32_16x16x32_bf16 v[114:117], v[178:181], v[190:193], v[114:117]
	v_mfma_f32_16x16x32_bf16 v[106:109], v[170:173], v[198:201], v[106:109]
	v_mfma_f32_16x16x32_bf16 v[98:101], v[178:181], v[198:201], v[98:101]
	v_mfma_f32_16x16x32_bf16 v[90:93], v[170:173], v[230:233], v[90:93]
	v_mfma_f32_16x16x32_bf16 v[82:85], v[178:181], v[230:233], v[82:85]
	v_mfma_f32_16x16x32_bf16 v[78:81], v[170:173], v[238:241], v[78:81]
	v_mfma_f32_16x16x32_bf16 v[74:77], v[178:181], v[238:241], v[74:77]
	s_setprio 0
	s_barrier
	s_add_i32 s41, s41, s24
	v_lshl_add_u64 v[202:203], s[18:19], 0, v[34:35]
	s_mov_b32 m0, s41
	ds_read_b128 v[186:189], v153 offset:16384
	ds_read_b128 v[190:193], v153 offset:17408
	ds_read_b128 v[194:197], v153 offset:18432
	ds_read_b128 v[198:201], v153 offset:19456
	ds_read_b128 v[226:229], v153 offset:20480
	ds_read_b128 v[230:233], v153 offset:21504
	ds_read_b128 v[234:237], v153 offset:22528
	ds_read_b128 v[238:241], v153 offset:23552
	global_load_lds_dwordx4 v[202:203], off
	s_add_i32 m0, s41, 0x2000
	s_add_u32 s42, s18, 0x40000
	v_lshl_add_u64 v[208:209], s[18:19], 0, v[36:37]
	s_addc_u32 s43, s19, 0
	s_add_i32 s41, s44, s24
	global_load_lds_dwordx4 v[208:209], off
	v_lshl_add_u64 v[210:211], s[42:43], 0, v[34:35]
	s_mov_b32 m0, s41
	v_lshl_add_u64 v[218:219], s[20:21], 0, v[138:139]
	global_load_lds_dwordx4 v[210:211], off
	v_lshl_add_u64 v[210:211], s[42:43], 0, v[36:37]
	s_add_i32 m0, s41, 0x2000
	s_nop 0
	global_load_lds_dwordx4 v[210:211], off
	v_lshl_add_u64 v[210:211], s[20:21], 0, v[140:141]
	s_mov_b32 m0, s25
	s_nop 0
	global_load_lds_dwordx4 v[210:211], off
	s_mov_b32 m0, s26
	s_nop 0
	global_load_lds_dwordx4 v[218:219], off
	s_waitcnt vmcnt(8)
	s_waitcnt lgkmcnt(0)
	s_barrier
; #define PG8_STAGE(bufoff, gbase, voff) do { _Pragma("unroll") for (int _i = 0; _i < 2; ++_i) \
;         __builtin_amdgcn_global_load_lds((const unsigned*)((const char*)(gbase) + (voff)[_i]), (PG8_LAS unsigned*)(lds + (bufoff) + ldsw + _i * 8192), 16, 0, 0); } while (0)
; #define PG8_LDA(dst, b, h) do { _Pragma("unroll") for (int m = 0; m < 4; ++m) _Pragma("unroll") for (int k = 0; k < 2; ++k) dst[m][k] = *(const PG8_LAS bf16x8*)(lds + PG8_SA(b, h) + aoff + m * 2048 + k * 1024); } while (0)
; #define PG8_LDB(dst, b, h) do { _Pragma("unroll") for (int n = 0; n < 2; ++n) _Pragma("unroll") for (int k = 0; k < 2; ++k) dst[n][k] = *(const PG8_LAS bf16x8*)(lds + PG8_SB(b, h) + boff + n * 2048 + k * 1024); } while (0)
; #define PG8_MMA(ai, bj, At, Bt) do { __builtin_amdgcn_s_setprio(1); _Pragma("unroll") for (int m = 0; m < 4; ++m) _Pragma("unroll") for (int n = 0; n < 2; ++n) _Pragma("unroll") for (int k = 0; k < 2; ++k) \
;         acc[ai][bj][m][n] = __builtin_amdgcn_mfma_f32_16x16x32_bf16(Bt[n][k], At[m][k], acc[ai][bj][m][n], 0, 0, 0); __builtin_amdgcn_s_setprio(0); } while (0)
; #define PG8_WAIT_V(n) asm volatile("s_waitcnt vmcnt(" #n ")" ::: "memory")
; #define PG8_WAIT_L(n) asm volatile("s_waitcnt lgkmcnt(" #n ")" ::: "memory")
; #define PG8_BAR __builtin_amdgcn_s_barrier()
; #define PG8_SCHED __builtin_amdgcn_sched_barrier(0)
; template <class Epi, class Sched, bool ALIGN_EPI = false, bool SP2 = false>
; __device__ __forceinline__ void gemm_phase(PG8_LAS unsigned char* lds, const Gemm g, const Sched& S, const Epi& E) {
;     ...
;             PG8_WAIT_V(8); PG8_WAIT_L(0); PG8_BAR; PG8_MMA(1, 0, At, B0); PG8_MMA(1, 1, At, B1); PG8_BAR; PG8_SCHED;
;             PG8_LDB(B0, 1, 0); PG8_LDB(B1, 1, 1); PG8_SCHED; PG8_LDA(At, 1, 0); PG8_STAGE(PG8_SA(0, 1), a2 + hstep, voffA);
;             PG8_WAIT_V(8); PG8_WAIT_L(0); PG8_BAR; PG8_MMA(0, 0, At, B0); PG8_MMA(0, 1, At, B1); PG8_BAR; PG8_SCHED;
;             PG8_LDA(At, 1, 1); PG8_STAGE(PG8_SB(1, 0), b3, voffB); PG8_STAGE(PG8_SB(1, 1), b3 + hstep, voffB); PG8_STAGE(PG8_SA(1, 0), a3, voffA);
	s_setprio 1
	s_waitcnt lgkmcnt(0)
	v_mfma_f32_16x16x32_bf16 v[70:73], v[146:149], v[186:189], 0
	v_mfma_f32_16x16x32_bf16 v[66:69], v[158:161], v[186:189], 0
	v_mfma_f32_16x16x32_bf16 v[62:65], v[146:149], v[194:197], 0
	v_mfma_f32_16x16x32_bf16 v[54:57], v[158:161], v[194:197], 0
	v_mfma_f32_16x16x32_bf16 v[46:49], v[146:149], v[226:229], 0
	v_mfma_f32_16x16x32_bf16 v[30:33], v[158:161], v[226:229], 0
	v_mfma_f32_16x16x32_bf16 v[22:25], v[146:149], v[234:237], 0
	v_mfma_f32_16x16x32_bf16 v[14:17], v[158:161], v[234:237], 0
	v_mfma_f32_16x16x32_bf16 v[70:73], v[154:157], v[190:193], v[70:73]
	v_mfma_f32_16x16x32_bf16 v[66:69], v[162:165], v[190:193], v[66:69]
	v_mfma_f32_16x16x32_bf16 v[62:65], v[154:157], v[198:201], v[62:65]
	v_mfma_f32_16x16x32_bf16 v[54:57], v[162:165], v[198:201], v[54:57]
	v_mfma_f32_16x16x32_bf16 v[46:49], v[154:157], v[230:233], v[46:49]
	v_mfma_f32_16x16x32_bf16 v[30:33], v[162:165], v[230:233], v[30:33]
	v_mfma_f32_16x16x32_bf16 v[22:25], v[154:157], v[238:241], v[22:25]
	v_mfma_f32_16x16x32_bf16 v[14:17], v[162:165], v[238:241], v[14:17]
	s_setprio 0
	s_setprio 1
	v_mfma_f32_16x16x32_bf16 v[58:61], v[166:169], v[186:189], 0
	v_mfma_f32_16x16x32_bf16 v[50:53], v[174:177], v[186:189], 0
	v_mfma_f32_16x16x32_bf16 v[42:45], v[166:169], v[194:197], 0
	v_mfma_f32_16x16x32_bf16 v[26:29], v[174:177], v[194:197], 0
	v_mfma_f32_16x16x32_bf16 v[18:21], v[166:169], v[226:229], 0
	v_mfma_f32_16x16x32_bf16 v[10:13], v[174:177], v[226:229], 0
	v_mfma_f32_16x16x32_bf16 v[6:9], v[166:169], v[234:237], 0
	v_mfma_f32_16x16x32_bf16 v[2:5], v[174:177], v[234:237], 0
	v_mfma_f32_16x16x32_bf16 v[58:61], v[170:173], v[190:193], v[58:61]
	v_mfma_f32_16x16x32_bf16 v[50:53], v[178:181], v[190:193], v[50:53]
	v_mfma_f32_16x16x32_bf16 v[42:45], v[170:173], v[198:201], v[42:45]
	v_mfma_f32_16x16x32_bf16 v[26:29], v[178:181], v[198:201], v[26:29]
	v_mfma_f32_16x16x32_bf16 v[18:21], v[170:173], v[230:233], v[18:21]
	v_mfma_f32_16x16x32_bf16 v[10:13], v[178:181], v[230:233], v[10:13]
	v_mfma_f32_16x16x32_bf16 v[6:9], v[170:173], v[238:241], v[6:9]
	v_mfma_f32_16x16x32_bf16 v[2:5], v[178:181], v[238:241], v[2:5]
	s_setprio 0
	s_barrier
	s_add_i32 s41, 0, 0x18000
	v_add_u32_e32 v38, s41, v151
	s_add_i32 s42, 0, 0x1c000
	ds_read_b128 v[146:149], v38
	ds_read_b128 v[154:157], v38 offset:1024
	ds_read_b128 v[158:161], v38 offset:2048
	ds_read_b128 v[162:165], v38 offset:3072
	v_add_u32_e32 v38, s42, v151
	ds_read_b128 v[166:169], v38
	ds_read_b128 v[170:173], v38 offset:1024
	ds_read_b128 v[174:177], v38 offset:2048
	ds_read_b128 v[178:181], v38 offset:3072
	s_add_u32 s20, s20, 0x40000
	s_addc_u32 s21, s21, 0
	s_mov_b32 m0, s27
	v_lshl_add_u64 v[220:221], s[20:21], 0, v[140:141]
	ds_read_b128 v[186:189], v153 offset:32768
	ds_read_b128 v[190:193], v153 offset:33792
	ds_read_b128 v[194:197], v153 offset:34816
	ds_read_b128 v[198:201], v153 offset:35840
	ds_read_b128 v[226:229], v153 offset:36864
	ds_read_b128 v[230:233], v153 offset:37888
	ds_read_b128 v[234:237], v153 offset:38912
	ds_read_b128 v[238:241], v153 offset:39936
	global_load_lds_dwordx4 v[220:221], off
	v_lshl_add_u64 v[220:221], s[20:21], 0, v[138:139]
	s_mov_b32 m0, s28
	s_nop 0
	global_load_lds_dwordx4 v[220:221], off
	s_waitcnt vmcnt(8)
	s_waitcnt lgkmcnt(0)
	s_barrier
	s_setprio 1
	s_waitcnt lgkmcnt(0)
	v_mfma_f32_16x16x32_bf16 v[134:137], v[146:149], v[186:189], v[134:137]
	v_mfma_f32_16x16x32_bf16 v[130:133], v[158:161], v[186:189], v[130:133]
	v_mfma_f32_16x16x32_bf16 v[126:129], v[146:149], v[194:197], v[126:129]
	v_mfma_f32_16x16x32_bf16 v[118:121], v[158:161], v[194:197], v[118:121]
	v_mfma_f32_16x16x32_bf16 v[110:113], v[146:149], v[226:229], v[110:113]
	v_mfma_f32_16x16x32_bf16 v[102:105], v[158:161], v[226:229], v[102:105]
	v_mfma_f32_16x16x32_bf16 v[94:97], v[146:149], v[234:237], v[94:97]
	v_mfma_f32_16x16x32_bf16 v[86:89], v[158:161], v[234:237], v[86:89]
	v_mfma_f32_16x16x32_bf16 v[134:137], v[154:157], v[190:193], v[134:137]
	v_mfma_f32_16x16x32_bf16 v[130:133], v[162:165], v[190:193], v[130:133]
	v_mfma_f32_16x16x32_bf16 v[126:129], v[154:157], v[198:201], v[126:129]
	v_mfma_f32_16x16x32_bf16 v[118:121], v[162:165], v[198:201], v[118:121]
	v_mfma_f32_16x16x32_bf16 v[110:113], v[154:157], v[230:233], v[110:113]
	v_mfma_f32_16x16x32_bf16 v[102:105], v[162:165], v[230:233], v[102:105]
	v_mfma_f32_16x16x32_bf16 v[94:97], v[154:157], v[238:241], v[94:97]
	v_mfma_f32_16x16x32_bf16 v[86:89], v[162:165], v[238:241], v[86:89]
	s_setprio 0
	s_setprio 1
	v_mfma_f32_16x16x32_bf16 v[122:125], v[166:169], v[186:189], v[122:125]
	v_mfma_f32_16x16x32_bf16 v[114:117], v[174:177], v[186:189], v[114:117]
	v_mfma_f32_16x16x32_bf16 v[106:109], v[166:169], v[194:197], v[106:109]
	v_mfma_f32_16x16x32_bf16 v[98:101], v[174:177], v[194:197], v[98:101]
	v_mfma_f32_16x16x32_bf16 v[90:93], v[166:169], v[226:229], v[90:93]
	v_mfma_f32_16x16x32_bf16 v[82:85], v[174:177], v[226:229], v[82:85]
	v_mfma_f32_16x16x32_bf16 v[78:81], v[166:169], v[234:237], v[78:81]
	v_mfma_f32_16x16x32_bf16 v[74:77], v[174:177], v[234:237], v[74:77]
	v_mfma_f32_16x16x32_bf16 v[122:125], v[170:173], v[190:193], v[122:125]
	v_mfma_f32_16x16x32_bf16 v[114:117], v[178:181], v[190:193], v[114:117]
	v_mfma_f32_16x16x32_bf16 v[106:109], v[170:173], v[198:201], v[106:109]
	v_mfma_f32_16x16x32_bf16 v[98:101], v[178:181], v[198:201], v[98:101]
	v_mfma_f32_16x16x32_bf16 v[90:93], v[170:173], v[230:233], v[90:93]
	v_mfma_f32_16x16x32_bf16 v[82:85], v[178:181], v[230:233], v[82:85]
	v_mfma_f32_16x16x32_bf16 v[78:81], v[170:173], v[238:241], v[78:81]
	v_mfma_f32_16x16x32_bf16 v[74:77], v[178:181], v[238:241], v[74:77]
	s_setprio 0
	s_barrier
; #define PG8_STAGE(bufoff, gbase, voff) do { _Pragma("unroll") for (int _i = 0; _i < 2; ++_i) \
;         __builtin_amdgcn_global_load_lds((const unsigned*)((const char*)(gbase) + (voff)[_i]), (PG8_LAS unsigned*)(lds + (bufoff) + ldsw + _i * 8192), 16, 0, 0); } while (0)
; #define PG8_LDA(dst, b, h) do { _Pragma("unroll") for (int m = 0; m < 4; ++m) _Pragma("unroll") for (int k = 0; k < 2; ++k) dst[m][k] = *(const PG8_LAS bf16x8*)(lds + PG8_SA(b, h) + aoff + m * 2048 + k * 1024); } while (0)
; #define PG8_MMA(ai, bj, At, Bt) do { __builtin_amdgcn_s_setprio(1); _Pragma("unroll") for (int m = 0; m < 4; ++m) _Pragma("unroll") for (int n = 0; n < 2; ++n) _Pragma("unroll") for (int k = 0; k < 2; ++k) \
;         acc[ai][bj][m][n] = __builtin_amdgcn_mfma_f32_16x16x32_bf16(Bt[n][k], At[m][k], acc[ai][bj][m][n], 0, 0, 0); __builtin_amdgcn_s_setprio(0); } while (0)
; #define PG8_WAIT_V(n) asm volatile("s_waitcnt vmcnt(" #n ")" ::: "memory")
; #define PG8_WAIT_L(n) asm volatile("s_waitcnt lgkmcnt(" #n ")" ::: "memory")
; #define PG8_BAR __builtin_amdgcn_s_barrier()
; #define PG8_SCHED __builtin_amdgcn_sched_barrier(0)
; template <class Epi, class Sched, bool ALIGN_EPI = false, bool SP2 = false>
; __device__ __forceinline__ void gemm_phase(PG8_LAS unsigned char* lds, const Gemm g, const Sched& S, const Epi& E) {
;     ...
;             PG8_LDA(At, 1, 1); PG8_STAGE(PG8_SB(1, 0), b3, voffB); PG8_STAGE(PG8_SB(1, 1), b3 + hstep, voffB); PG8_STAGE(PG8_SA(1, 0), a3, voffA);
;             PG8_WAIT_V(8); PG8_WAIT_L(0); PG8_BAR; PG8_MMA(1, 0, At, B0); PG8_MMA(1, 1, At, B1); PG8_BAR; PG8_SCHED;
	s_add_i32 s20, s41, s24
	v_lshl_add_u64 v[202:203], v[202:203], 0, s[70:71]
	s_mov_b32 m0, s20
	ds_read_b128 v[186:189], v153 offset:49152
	ds_read_b128 v[190:193], v153 offset:50176
	ds_read_b128 v[194:197], v153 offset:51200
	ds_read_b128 v[198:201], v153 offset:52224
	ds_read_b128 v[226:229], v153 offset:53248
	ds_read_b128 v[230:233], v153 offset:54272
	ds_read_b128 v[234:237], v153 offset:55296
	ds_read_b128 v[238:241], v153 offset:56320
	global_load_lds_dwordx4 v[202:203], off
	s_add_i32 m0, s20, 0x2000
	s_add_u32 s18, s18, 0x40080
	v_lshl_add_u64 v[202:203], v[208:209], 0, s[70:71]
	s_addc_u32 s19, s19, 0
	s_add_i32 s20, s42, s24
	global_load_lds_dwordx4 v[202:203], off
	v_lshl_add_u64 v[202:203], s[18:19], 0, v[34:35]
	s_mov_b32 m0, s20
	s_nop 0
	global_load_lds_dwordx4 v[202:203], off
	v_lshl_add_u64 v[202:203], s[18:19], 0, v[36:37]
	s_add_i32 m0, s20, 0x2000
	s_nop 0
	global_load_lds_dwordx4 v[202:203], off
	v_lshl_add_u64 v[202:203], v[210:211], 0, s[70:71]
	s_mov_b32 m0, s29
	s_nop 0
	global_load_lds_dwordx4 v[202:203], off
	v_lshl_add_u64 v[202:203], v[218:219], 0, s[70:71]
	s_mov_b32 m0, s30
	s_nop 0
	global_load_lds_dwordx4 v[202:203], off
	s_waitcnt vmcnt(8)
	s_waitcnt lgkmcnt(0)
	s_barrier
	s_setprio 1
	s_waitcnt lgkmcnt(0)
	v_mfma_f32_16x16x32_bf16 v[70:73], v[146:149], v[186:189], v[70:73]
	v_mfma_f32_16x16x32_bf16 v[66:69], v[158:161], v[186:189], v[66:69]
	v_mfma_f32_16x16x32_bf16 v[62:65], v[146:149], v[194:197], v[62:65]
	v_mfma_f32_16x16x32_bf16 v[54:57], v[158:161], v[194:197], v[54:57]
	v_mfma_f32_16x16x32_bf16 v[46:49], v[146:149], v[226:229], v[46:49]
	v_mfma_f32_16x16x32_bf16 v[30:33], v[158:161], v[226:229], v[30:33]
	v_mfma_f32_16x16x32_bf16 v[22:25], v[146:149], v[234:237], v[22:25]
	v_mfma_f32_16x16x32_bf16 v[14:17], v[158:161], v[234:237], v[14:17]
	v_mfma_f32_16x16x32_bf16 v[70:73], v[154:157], v[190:193], v[70:73]
	v_mfma_f32_16x16x32_bf16 v[66:69], v[162:165], v[190:193], v[66:69]
	v_mfma_f32_16x16x32_bf16 v[62:65], v[154:157], v[198:201], v[62:65]
	v_mfma_f32_16x16x32_bf16 v[54:57], v[162:165], v[198:201], v[54:57]
	v_mfma_f32_16x16x32_bf16 v[46:49], v[154:157], v[230:233], v[46:49]
	v_mfma_f32_16x16x32_bf16 v[30:33], v[162:165], v[230:233], v[30:33]
	v_mfma_f32_16x16x32_bf16 v[22:25], v[154:157], v[238:241], v[22:25]
	v_mfma_f32_16x16x32_bf16 v[14:17], v[162:165], v[238:241], v[14:17]
	s_setprio 0
	s_setprio 1
	v_mfma_f32_16x16x32_bf16 v[58:61], v[166:169], v[186:189], v[58:61]
	v_mfma_f32_16x16x32_bf16 v[50:53], v[174:177], v[186:189], v[50:53]
	v_mfma_f32_16x16x32_bf16 v[42:45], v[166:169], v[194:197], v[42:45]
	v_mfma_f32_16x16x32_bf16 v[26:29], v[174:177], v[194:197], v[26:29]
	v_mfma_f32_16x16x32_bf16 v[18:21], v[166:169], v[226:229], v[18:21]
	v_mfma_f32_16x16x32_bf16 v[10:13], v[174:177], v[226:229], v[10:13]
	v_mfma_f32_16x16x32_bf16 v[6:9], v[166:169], v[234:237], v[6:9]
	v_mfma_f32_16x16x32_bf16 v[2:5], v[174:177], v[234:237], v[2:5]
	v_mfma_f32_16x16x32_bf16 v[58:61], v[170:173], v[190:193], v[58:61]
	v_mfma_f32_16x16x32_bf16 v[50:53], v[178:181], v[190:193], v[50:53]
	v_mfma_f32_16x16x32_bf16 v[42:45], v[170:173], v[198:201], v[42:45]
	v_mfma_f32_16x16x32_bf16 v[26:29], v[178:181], v[198:201], v[26:29]
	v_mfma_f32_16x16x32_bf16 v[18:21], v[170:173], v[230:233], v[18:21]
	v_mfma_f32_16x16x32_bf16 v[10:13], v[178:181], v[230:233], v[10:13]
	v_mfma_f32_16x16x32_bf16 v[6:9], v[170:173], v[238:241], v[6:9]
	v_mfma_f32_16x16x32_bf16 v[2:5], v[178:181], v[238:241], v[2:5]
	s_setprio 0
	s_barrier
	s_add_i32 s40, s40, 2
	s_add_u32 s16, s16, 0x100
	s_addc_u32 s17, s17, 0
	s_add_u32 s38, s38, 0x100
	s_addc_u32 s39, s39, 0
	s_cmp_gt_u32 s40, 13

;     __device__ __forceinline__ long arow(int pm) const { return (long)pm * BM; }
;     __device__ __forceinline__ long arow(int pm) const { if (pm < 132) { const int b = pm / 33, i = pm - b * 33; return (long)b * 8192 + 254 * i - 1; } return 32768 + (long)(pm - 132) * 256; }
;     __device__ __forceinline__ bool next(int i, Unit& u) const { if (i > 0) return false; u.pm = pm; u.pn = pn; return true; }
;     __device__ __forceinline__ long arow(int p) const { return (long)p * BM; }
; #define PG8_LDA(dst, b, h) do { _Pragma("unroll") for (int m = 0; m < 4; ++m) _Pragma("unroll") for (int k = 0; k < 2; ++k) dst[m][k] = *(const PG8_LAS bf16x8*)(lds + PG8_SA(b, h) + aoff + m * 2048 + k * 1024); } while (0)
; template <class Epi, class Sched, bool ALIGN_EPI = false, bool SP2 = false>
; __device__ __forceinline__ void gemm_phase(PG8_LAS unsigned char* lds, const Gemm g, const Sched& S, const Epi& E) {
;     ...
;         const bool has_next = S.next(ui + 1, nxt);
;         const char* nA = has_next ? (const char*)g.A + S.arow(nxt.pm) * rowb : cA; const char* nB = has_next ? (const char*)g.Bt + (size_t)nxt.pn * tstep : cB;
;         for (int t = 0; t < nt; t += 2) {
;             const bool last = (t == nt - 2);
;             const char* a1 = cA + (size_t)(t + 1) * kstep;
;             const char* a2 = last ? nA : cA + (size_t)(t + 2) * kstep; const char* b2 = last ? nB : cB + (size_t)(t + 2) * kstep;
;             const char* a3 = a2 + kstep; const char* b3 = b2 + kstep;
;             if (last && has_next) S.a_ready(nxt);
;             if constexpr (SP2) {
;             PG8_LDB(B0, 0, 0); PG8_LDB(B1, 0, 1); PG8_SCHED; PG8_LDA(At, 0, 0); PG8_STAGE(PG8_SA(1, 1), a1 + hstep, voffA);
;             PG8_WAIT_V(8); PG8_WAIT_L(0); PG8_BAR; PG8_MMA(0, 0, At, B0); PG8_MMA(0, 1, At, B1); PG8_BAR; PG8_SCHED;
;             PG8_LDA(At, 0, 1); PG8_STAGE(PG8_SB(0, 0), b2, voffB); PG8_STAGE(PG8_SB(0, 1), b2 + hstep, voffB); PG8_STAGE(PG8_SA(0, 0), a2, voffA);
;             PG8_WAIT_V(8); PG8_WAIT_L(0); PG8_BAR; PG8_MMA(1, 0, At, B0); PG8_MMA(1, 1, At, B1); PG8_BAR; PG8_SCHED;
;     ...
;         for (int a = 0; a < 2; ++a)
; #pragma unroll
;             for (int b = 0; b < 2; ++b)
; #pragma unroll
;                 for (int m = 0; m < 4; ++m)
; #pragma unroll
;                     for (int n = 0; n < 2; ++n) acc[a][b][m][n] = (f32x4){0.f, 0.f, 0.f, 0.f};
.LBB0_541:
	s_ashr_i32 s9, s8, 31
	s_lshl_b64 s[10:11], s[8:9], 19
	s_add_u32 s10, s81, s10
	s_addc_u32 s11, s85, s11
	s_and_b64 s[12:13], s[4:5], exec
	s_cselect_b32 s9, s11, s17
	s_cselect_b32 s15, s10, s16
	s_ashr_i32 s7, s6, 31
	s_lshl_b64 s[12:13], s[6:7], 19
	s_add_u32 s12, s26, s12
	s_addc_u32 s13, s27, s13
	s_and_b64 s[20:21], s[4:5], exec
	s_cselect_b32 s7, s13, s19
	s_cselect_b32 s41, s12, s18
	s_add_u32 s42, s18, 0x100
	s_addc_u32 s43, s19, 0
	s_mov_b32 s44, -2
	s_add_u32 s18, s16, 0x100
	s_addc_u32 s19, s17, 0
	s_add_i32 s45, 0, 0x10000
	s_cmp_eq_u32 s44, 12
	s_cselect_b32 s23, s9, s19
	s_cselect_b32 s22, s15, s18
	v_add_u32_e32 v38, s45, v168
	s_cselect_b32 s21, s7, s43
	s_cselect_b32 s20, s41, s42
	s_add_i32 s46, 0, 0x14000
	ds_read_b128 v[138:141], v38
	ds_read_b128 v[162:165], v38 offset:1024
	ds_read_b128 v[172:175], v38 offset:2048
	ds_read_b128 v[176:179], v38 offset:3072
	v_add_u32_e32 v38, s46, v168
	ds_read_b128 v[186:189], v38
	ds_read_b128 v[190:193], v38 offset:1024
	ds_read_b128 v[194:197], v38 offset:2048
	ds_read_b128 v[198:201], v38 offset:3072
	v_lshl_add_u64 v[166:167], s[16:17], 0, v[158:159]
	s_add_i32 m0, s29, 0xc000
	ds_read_b128 v[226:229], v170
	ds_read_b128 v[230:233], v170 offset:1024
	ds_read_b128 v[234:237], v170 offset:2048
	ds_read_b128 v[238:241], v170 offset:3072
	ds_read_b128 v[242:245], v170 offset:4096
	ds_read_b128 v[246:249], v170 offset:5120
	ds_read_b128 v[218:221], v170 offset:6144
	ds_read_b128 v[208:211], v170 offset:7168
	global_load_lds_dwordx4 v[166:167], off
	v_lshl_add_u64 v[166:167], s[16:17], 0, v[160:161]
	s_add_i32 m0, s29, 0xe000
	s_nop 0
	global_load_lds_dwordx4 v[166:167], off
	s_waitcnt vmcnt(8)
	s_waitcnt lgkmcnt(0)
	s_barrier
	s_setprio 1
	s_waitcnt lgkmcnt(0)
	v_mfma_f32_16x16x32_bf16 v[134:137], v[138:141], v[226:229], 0
	v_mfma_f32_16x16x32_bf16 v[106:109], v[172:175], v[226:229], 0
	v_mfma_f32_16x16x32_bf16 v[130:133], v[138:141], v[234:237], 0
	v_mfma_f32_16x16x32_bf16 v[102:105], v[172:175], v[234:237], 0
	v_mfma_f32_16x16x32_bf16 v[126:129], v[138:141], v[242:245], 0
	v_mfma_f32_16x16x32_bf16 v[98:101], v[172:175], v[242:245], 0
	v_mfma_f32_16x16x32_bf16 v[122:125], v[138:141], v[218:221], 0
	v_mfma_f32_16x16x32_bf16 v[90:93], v[172:175], v[218:221], 0
	v_mfma_f32_16x16x32_bf16 v[134:137], v[162:165], v[230:233], v[134:137]
	v_mfma_f32_16x16x32_bf16 v[106:109], v[176:179], v[230:233], v[106:109]
	v_mfma_f32_16x16x32_bf16 v[130:133], v[162:165], v[238:241], v[130:133]
	v_mfma_f32_16x16x32_bf16 v[102:105], v[176:179], v[238:241], v[102:105]
	v_mfma_f32_16x16x32_bf16 v[126:129], v[162:165], v[246:249], v[126:129]
	v_mfma_f32_16x16x32_bf16 v[98:101], v[176:179], v[246:249], v[98:101]
	v_mfma_f32_16x16x32_bf16 v[122:125], v[162:165], v[208:211], v[122:125]
	v_mfma_f32_16x16x32_bf16 v[90:93], v[176:179], v[208:211], v[90:93]
	s_setprio 0
	s_setprio 1
	v_mfma_f32_16x16x32_bf16 v[82:85], v[186:189], v[226:229], 0
	v_mfma_f32_16x16x32_bf16 v[54:57], v[194:197], v[226:229], 0
	v_mfma_f32_16x16x32_bf16 v[74:77], v[186:189], v[234:237], 0
	v_mfma_f32_16x16x32_bf16 v[46:49], v[194:197], v[234:237], 0
	v_mfma_f32_16x16x32_bf16 v[66:69], v[186:189], v[242:245], 0
	v_mfma_f32_16x16x32_bf16 v[30:33], v[194:197], v[242:245], 0
	v_mfma_f32_16x16x32_bf16 v[58:61], v[186:189], v[218:221], 0
	v_mfma_f32_16x16x32_bf16 v[22:25], v[194:197], v[218:221], 0
	v_mfma_f32_16x16x32_bf16 v[82:85], v[190:193], v[230:233], v[82:85]
	v_mfma_f32_16x16x32_bf16 v[54:57], v[198:201], v[230:233], v[54:57]
	v_mfma_f32_16x16x32_bf16 v[74:77], v[190:193], v[238:241], v[74:77]
	v_mfma_f32_16x16x32_bf16 v[46:49], v[198:201], v[238:241], v[46:49]
	v_mfma_f32_16x16x32_bf16 v[66:69], v[190:193], v[246:249], v[66:69]
	v_mfma_f32_16x16x32_bf16 v[30:33], v[198:201], v[246:249], v[30:33]
	v_mfma_f32_16x16x32_bf16 v[58:61], v[190:193], v[208:211], v[58:61]
	v_mfma_f32_16x16x32_bf16 v[22:25], v[198:201], v[208:211], v[22:25]
	s_setprio 0
	s_barrier
	s_add_i32 s16, s45, s28
	v_lshl_add_u64 v[166:167], s[20:21], 0, v[34:35]
	s_mov_b32 m0, s16
	ds_read_b128 v[208:211], v170 offset:16384
	ds_read_b128 v[218:221], v170 offset:17408
	ds_read_b128 v[226:229], v170 offset:18432
	ds_read_b128 v[230:233], v170 offset:19456
	ds_read_b128 v[234:237], v170 offset:20480
	ds_read_b128 v[238:241], v170 offset:21504
	ds_read_b128 v[242:245], v170 offset:22528
	ds_read_b128 v[246:249], v170 offset:23552
	global_load_lds_dwordx4 v[166:167], off
	s_add_i32 m0, s16, 0x2000
	s_add_u32 s16, s20, 0x40000
	v_lshl_add_u64 v[180:181], s[20:21], 0, v[36:37]
	s_addc_u32 s17, s21, 0
	s_add_i32 s45, s46, s28
	global_load_lds_dwordx4 v[180:181], off
	v_lshl_add_u64 v[202:203], s[16:17], 0, v[34:35]
	s_mov_b32 m0, s45
	v_lshl_add_u64 v[250:251], s[22:23], 0, v[36:37]
	global_load_lds_dwordx4 v[202:203], off
	v_lshl_add_u64 v[202:203], s[16:17], 0, v[36:37]
	s_add_i32 m0, s45, 0x2000
	s_nop 0
	global_load_lds_dwordx4 v[202:203], off
	v_lshl_add_u64 v[202:203], s[22:23], 0, v[34:35]
	s_mov_b32 m0, s29
	s_nop 0
	global_load_lds_dwordx4 v[202:203], off
	s_mov_b32 m0, s30
	s_nop 0
	global_load_lds_dwordx4 v[250:251], off
	s_waitcnt vmcnt(8)
	s_waitcnt lgkmcnt(0)
	s_barrier
; #define PG8_STAGE(bufoff, gbase, voff) do { _Pragma("unroll") for (int _i = 0; _i < 2; ++_i) \
;         __builtin_amdgcn_global_load_lds((const unsigned*)((const char*)(gbase) + (voff)[_i]), (PG8_LAS unsigned*)(lds + (bufoff) + ldsw + _i * 8192), 16, 0, 0); } while (0)
; #define PG8_LDA(dst, b, h) do { _Pragma("unroll") for (int m = 0; m < 4; ++m) _Pragma("unroll") for (int k = 0; k < 2; ++k) dst[m][k] = *(const PG8_LAS bf16x8*)(lds + PG8_SA(b, h) + aoff + m * 2048 + k * 1024); } while (0)
; #define PG8_LDB(dst, b, h) do { _Pragma("unroll") for (int n = 0; n < 2; ++n) _Pragma("unroll") for (int k = 0; k < 2; ++k) dst[n][k] = *(const PG8_LAS bf16x8*)(lds + PG8_SB(b, h) + boff + n * 2048 + k * 1024); } while (0)
; #define PG8_MMA(ai, bj, At, Bt) do { __builtin_amdgcn_s_setprio(1); _Pragma("unroll") for (int m = 0; m < 4; ++m) _Pragma("unroll") for (int n = 0; n < 2; ++n) _Pragma("unroll") for (int k = 0; k < 2; ++k) \
;         acc[ai][bj][m][n] = __builtin_amdgcn_mfma_f32_16x16x32_bf16(Bt[n][k], At[m][k], acc[ai][bj][m][n], 0, 0, 0); __builtin_amdgcn_s_setprio(0); } while (0)
; #define PG8_WAIT_V(n) asm volatile("s_waitcnt vmcnt(" #n ")" ::: "memory")
; #define PG8_WAIT_L(n) asm volatile("s_waitcnt lgkmcnt(" #n ")" ::: "memory")
; #define PG8_BAR __builtin_amdgcn_s_barrier()
; #define PG8_SCHED __builtin_amdgcn_sched_barrier(0)
; template <class Epi, class Sched, bool ALIGN_EPI = false, bool SP2 = false>
; __device__ __forceinline__ void gemm_phase(PG8_LAS unsigned char* lds, const Gemm g, const Sched& S, const Epi& E) {
;     ...
;             PG8_WAIT_V(8); PG8_WAIT_L(0); PG8_BAR; PG8_MMA(1, 0, At, B0); PG8_MMA(1, 1, At, B1); PG8_BAR; PG8_SCHED;
;             PG8_LDB(B0, 1, 0); PG8_LDB(B1, 1, 1); PG8_SCHED; PG8_LDA(At, 1, 0); PG8_STAGE(PG8_SA(0, 1), a2 + hstep, voffA);
;             PG8_WAIT_V(8); PG8_WAIT_L(0); PG8_BAR; PG8_MMA(0, 0, At, B0); PG8_MMA(0, 1, At, B1); PG8_BAR; PG8_SCHED;
;             PG8_LDA(At, 1, 1); PG8_STAGE(PG8_SB(1, 0), b3, voffB); PG8_STAGE(PG8_SB(1, 1), b3 + hstep, voffB); PG8_STAGE(PG8_SA(1, 0), a3, voffA);
	s_setprio 1
	s_waitcnt lgkmcnt(0)
	v_mfma_f32_16x16x32_bf16 v[118:121], v[138:141], v[208:211], 0
	v_mfma_f32_16x16x32_bf16 v[86:89], v[172:175], v[208:211], 0
	v_mfma_f32_16x16x32_bf16 v[114:117], v[138:141], v[226:229], 0
	v_mfma_f32_16x16x32_bf16 v[78:81], v[172:175], v[226:229], 0
	v_mfma_f32_16x16x32_bf16 v[110:113], v[138:141], v[234:237], 0
	v_mfma_f32_16x16x32_bf16 v[70:73], v[172:175], v[234:237], 0
	v_mfma_f32_16x16x32_bf16 v[94:97], v[138:141], v[242:245], 0
	v_mfma_f32_16x16x32_bf16 v[62:65], v[172:175], v[242:245], 0
	v_mfma_f32_16x16x32_bf16 v[118:121], v[162:165], v[218:221], v[118:121]
	v_mfma_f32_16x16x32_bf16 v[86:89], v[176:179], v[218:221], v[86:89]
	v_mfma_f32_16x16x32_bf16 v[114:117], v[162:165], v[230:233], v[114:117]
	v_mfma_f32_16x16x32_bf16 v[78:81], v[176:179], v[230:233], v[78:81]
	v_mfma_f32_16x16x32_bf16 v[110:113], v[162:165], v[238:241], v[110:113]
	v_mfma_f32_16x16x32_bf16 v[70:73], v[176:179], v[238:241], v[70:73]
	v_mfma_f32_16x16x32_bf16 v[94:97], v[162:165], v[246:249], v[94:97]
	v_mfma_f32_16x16x32_bf16 v[62:65], v[176:179], v[246:249], v[62:65]
	s_setprio 0
	s_setprio 1
	v_mfma_f32_16x16x32_bf16 v[50:53], v[186:189], v[208:211], 0
	v_mfma_f32_16x16x32_bf16 v[14:17], v[194:197], v[208:211], 0
	v_mfma_f32_16x16x32_bf16 v[42:45], v[186:189], v[226:229], 0
	v_mfma_f32_16x16x32_bf16 v[10:13], v[194:197], v[226:229], 0
	v_mfma_f32_16x16x32_bf16 v[26:29], v[186:189], v[234:237], 0
	v_mfma_f32_16x16x32_bf16 v[6:9], v[194:197], v[234:237], 0
	v_mfma_f32_16x16x32_bf16 v[18:21], v[186:189], v[242:245], 0
	v_mfma_f32_16x16x32_bf16 v[2:5], v[194:197], v[242:245], 0
	v_mfma_f32_16x16x32_bf16 v[50:53], v[190:193], v[218:221], v[50:53]
	v_mfma_f32_16x16x32_bf16 v[14:17], v[198:201], v[218:221], v[14:17]
	v_mfma_f32_16x16x32_bf16 v[42:45], v[190:193], v[230:233], v[42:45]
	v_mfma_f32_16x16x32_bf16 v[10:13], v[198:201], v[230:233], v[10:13]
	v_mfma_f32_16x16x32_bf16 v[26:29], v[190:193], v[238:241], v[26:29]
	v_mfma_f32_16x16x32_bf16 v[6:9], v[198:201], v[238:241], v[6:9]
	v_mfma_f32_16x16x32_bf16 v[18:21], v[190:193], v[246:249], v[18:21]
	v_mfma_f32_16x16x32_bf16 v[2:5], v[198:201], v[246:249], v[2:5]
	s_setprio 0
	s_barrier
	s_add_i32 s45, 0, 0x18000
	v_add_u32_e32 v38, s45, v168
	s_add_i32 s46, 0, 0x1c000
	ds_read_b128 v[138:141], v38
	ds_read_b128 v[162:165], v38 offset:1024
	ds_read_b128 v[172:175], v38 offset:2048
	ds_read_b128 v[176:179], v38 offset:3072
	v_add_u32_e32 v38, s46, v168
	ds_read_b128 v[186:189], v38
	ds_read_b128 v[190:193], v38 offset:1024
	ds_read_b128 v[194:197], v38 offset:2048
	ds_read_b128 v[198:201], v38 offset:3072
	s_add_u32 s16, s22, 0x40000
	s_addc_u32 s17, s23, 0
	s_mov_b32 m0, s31
	v_lshl_add_u64 v[212:213], s[16:17], 0, v[34:35]
	ds_read_b128 v[208:211], v170 offset:32768
	ds_read_b128 v[218:221], v170 offset:33792
	ds_read_b128 v[226:229], v170 offset:34816
	ds_read_b128 v[230:233], v170 offset:35840
	ds_read_b128 v[234:237], v170 offset:36864
	ds_read_b128 v[238:241], v170 offset:37888
	ds_read_b128 v[242:245], v170 offset:38912
	ds_read_b128 v[246:249], v170 offset:39936
	global_load_lds_dwordx4 v[212:213], off
	v_lshl_add_u64 v[212:213], s[16:17], 0, v[36:37]
	s_mov_b32 m0, s34
	s_nop 0
	global_load_lds_dwordx4 v[212:213], off
	s_waitcnt vmcnt(8)
	s_waitcnt lgkmcnt(0)
	s_barrier
	s_setprio 1
	s_waitcnt lgkmcnt(0)
	v_mfma_f32_16x16x32_bf16 v[134:137], v[138:141], v[208:211], v[134:137]
	v_mfma_f32_16x16x32_bf16 v[106:109], v[172:175], v[208:211], v[106:109]
	v_mfma_f32_16x16x32_bf16 v[130:133], v[138:141], v[226:229], v[130:133]
	v_mfma_f32_16x16x32_bf16 v[102:105], v[172:175], v[226:229], v[102:105]
	v_mfma_f32_16x16x32_bf16 v[126:129], v[138:141], v[234:237], v[126:129]
	v_mfma_f32_16x16x32_bf16 v[98:101], v[172:175], v[234:237], v[98:101]
	v_mfma_f32_16x16x32_bf16 v[122:125], v[138:141], v[242:245], v[122:125]
	v_mfma_f32_16x16x32_bf16 v[90:93], v[172:175], v[242:245], v[90:93]
	v_mfma_f32_16x16x32_bf16 v[134:137], v[162:165], v[218:221], v[134:137]
	v_mfma_f32_16x16x32_bf16 v[106:109], v[176:179], v[218:221], v[106:109]
	v_mfma_f32_16x16x32_bf16 v[130:133], v[162:165], v[230:233], v[130:133]
	v_mfma_f32_16x16x32_bf16 v[102:105], v[176:179], v[230:233], v[102:105]
	v_mfma_f32_16x16x32_bf16 v[126:129], v[162:165], v[238:241], v[126:129]
	v_mfma_f32_16x16x32_bf16 v[98:101], v[176:179], v[238:241], v[98:101]
	v_mfma_f32_16x16x32_bf16 v[122:125], v[162:165], v[246:249], v[122:125]
	v_mfma_f32_16x16x32_bf16 v[90:93], v[176:179], v[246:249], v[90:93]
	s_setprio 0
	s_setprio 1
	v_mfma_f32_16x16x32_bf16 v[82:85], v[186:189], v[208:211], v[82:85]
	v_mfma_f32_16x16x32_bf16 v[54:57], v[194:197], v[208:211], v[54:57]
	v_mfma_f32_16x16x32_bf16 v[74:77], v[186:189], v[226:229], v[74:77]
	v_mfma_f32_16x16x32_bf16 v[46:49], v[194:197], v[226:229], v[46:49]
	v_mfma_f32_16x16x32_bf16 v[66:69], v[186:189], v[234:237], v[66:69]
	v_mfma_f32_16x16x32_bf16 v[30:33], v[194:197], v[234:237], v[30:33]
	v_mfma_f32_16x16x32_bf16 v[58:61], v[186:189], v[242:245], v[58:61]
	v_mfma_f32_16x16x32_bf16 v[22:25], v[194:197], v[242:245], v[22:25]
	v_mfma_f32_16x16x32_bf16 v[82:85], v[190:193], v[218:221], v[82:85]
	v_mfma_f32_16x16x32_bf16 v[54:57], v[198:201], v[218:221], v[54:57]
	v_mfma_f32_16x16x32_bf16 v[74:77], v[190:193], v[230:233], v[74:77]
	v_mfma_f32_16x16x32_bf16 v[46:49], v[198:201], v[230:233], v[46:49]
	v_mfma_f32_16x16x32_bf16 v[66:69], v[190:193], v[238:241], v[66:69]
	v_mfma_f32_16x16x32_bf16 v[30:33], v[198:201], v[238:241], v[30:33]
	v_mfma_f32_16x16x32_bf16 v[58:61], v[190:193], v[246:249], v[58:61]
	v_mfma_f32_16x16x32_bf16 v[22:25], v[198:201], v[246:249], v[22:25]
	s_setprio 0
	s_barrier
; #define PG8_STAGE(bufoff, gbase, voff) do { _Pragma("unroll") for (int _i = 0; _i < 2; ++_i) \
;         __builtin_amdgcn_global_load_lds((const unsigned*)((const char*)(gbase) + (voff)[_i]), (PG8_LAS unsigned*)(lds + (bufoff) + ldsw + _i * 8192), 16, 0, 0); } while (0)
; #define PG8_LDA(dst, b, h) do { _Pragma("unroll") for (int m = 0; m < 4; ++m) _Pragma("unroll") for (int k = 0; k < 2; ++k) dst[m][k] = *(const PG8_LAS bf16x8*)(lds + PG8_SA(b, h) + aoff + m * 2048 + k * 1024); } while (0)
; #define PG8_MMA(ai, bj, At, Bt) do { __builtin_amdgcn_s_setprio(1); _Pragma("unroll") for (int m = 0; m < 4; ++m) _Pragma("unroll") for (int n = 0; n < 2; ++n) _Pragma("unroll") for (int k = 0; k < 2; ++k) \
;         acc[ai][bj][m][n] = __builtin_amdgcn_mfma_f32_16x16x32_bf16(Bt[n][k], At[m][k], acc[ai][bj][m][n], 0, 0, 0); __builtin_amdgcn_s_setprio(0); } while (0)
; #define PG8_WAIT_V(n) asm volatile("s_waitcnt vmcnt(" #n ")" ::: "memory")
; #define PG8_WAIT_L(n) asm volatile("s_waitcnt lgkmcnt(" #n ")" ::: "memory")
; #define PG8_BAR __builtin_amdgcn_s_barrier()
; #define PG8_SCHED __builtin_amdgcn_sched_barrier(0)
; template <class Epi, class Sched, bool ALIGN_EPI = false, bool SP2 = false>
; __device__ __forceinline__ void gemm_phase(PG8_LAS unsigned char* lds, const Gemm g, const Sched& S, const Epi& E) {
;     ...
;             PG8_LDA(At, 1, 1); PG8_STAGE(PG8_SB(1, 0), b3, voffB); PG8_STAGE(PG8_SB(1, 1), b3 + hstep, voffB); PG8_STAGE(PG8_SA(1, 0), a3, voffA);
;             PG8_WAIT_V(8); PG8_WAIT_L(0); PG8_BAR; PG8_MMA(1, 0, At, B0); PG8_MMA(1, 1, At, B1); PG8_BAR; PG8_SCHED;
	s_add_i32 s16, s45, s28
	v_lshl_add_u64 v[166:167], v[166:167], 0, s[70:71]
	s_mov_b32 m0, s16
	ds_read_b128 v[208:211], v170 offset:49152
	ds_read_b128 v[218:221], v170 offset:50176
	ds_read_b128 v[226:229], v170 offset:51200
	ds_read_b128 v[230:233], v170 offset:52224
	ds_read_b128 v[234:237], v170 offset:53248
	ds_read_b128 v[238:241], v170 offset:54272
	ds_read_b128 v[242:245], v170 offset:55296
	ds_read_b128 v[246:249], v170 offset:56320
	global_load_lds_dwordx4 v[166:167], off
	s_add_i32 m0, s16, 0x2000
	s_add_u32 s16, s20, 0x40080
	v_lshl_add_u64 v[166:167], v[180:181], 0, s[70:71]
	s_addc_u32 s17, s21, 0
	s_add_i32 s20, s46, s28
	global_load_lds_dwordx4 v[166:167], off
	v_lshl_add_u64 v[166:167], s[16:17], 0, v[34:35]
	s_mov_b32 m0, s20
	s_nop 0
	global_load_lds_dwordx4 v[166:167], off
	v_lshl_add_u64 v[166:167], s[16:17], 0, v[36:37]
	s_add_i32 m0, s20, 0x2000
	s_nop 0
	global_load_lds_dwordx4 v[166:167], off
	v_lshl_add_u64 v[166:167], v[202:203], 0, s[70:71]
	s_mov_b32 m0, s37
	s_nop 0
	global_load_lds_dwordx4 v[166:167], off
	v_lshl_add_u64 v[166:167], v[250:251], 0, s[70:71]
	s_mov_b32 m0, s38
	s_nop 0
	global_load_lds_dwordx4 v[166:167], off
	s_waitcnt vmcnt(8)
	s_waitcnt lgkmcnt(0)
	s_barrier
	s_setprio 1
	s_waitcnt lgkmcnt(0)
	v_mfma_f32_16x16x32_bf16 v[118:121], v[138:141], v[208:211], v[118:121]
	v_mfma_f32_16x16x32_bf16 v[86:89], v[172:175], v[208:211], v[86:89]
	v_mfma_f32_16x16x32_bf16 v[114:117], v[138:141], v[226:229], v[114:117]
	v_mfma_f32_16x16x32_bf16 v[78:81], v[172:175], v[226:229], v[78:81]
	v_mfma_f32_16x16x32_bf16 v[110:113], v[138:141], v[234:237], v[110:113]
	v_mfma_f32_16x16x32_bf16 v[70:73], v[172:175], v[234:237], v[70:73]
	v_mfma_f32_16x16x32_bf16 v[94:97], v[138:141], v[242:245], v[94:97]
	v_mfma_f32_16x16x32_bf16 v[62:65], v[172:175], v[242:245], v[62:65]
	v_mfma_f32_16x16x32_bf16 v[118:121], v[162:165], v[218:221], v[118:121]
	v_mfma_f32_16x16x32_bf16 v[86:89], v[176:179], v[218:221], v[86:89]
	v_mfma_f32_16x16x32_bf16 v[114:117], v[162:165], v[230:233], v[114:117]
	v_mfma_f32_16x16x32_bf16 v[78:81], v[176:179], v[230:233], v[78:81]
	v_mfma_f32_16x16x32_bf16 v[110:113], v[162:165], v[238:241], v[110:113]
	v_mfma_f32_16x16x32_bf16 v[70:73], v[176:179], v[238:241], v[70:73]
	v_mfma_f32_16x16x32_bf16 v[94:97], v[162:165], v[246:249], v[94:97]
	v_mfma_f32_16x16x32_bf16 v[62:65], v[176:179], v[246:249], v[62:65]
	s_setprio 0
	s_setprio 1
	v_mfma_f32_16x16x32_bf16 v[50:53], v[186:189], v[208:211], v[50:53]
	v_mfma_f32_16x16x32_bf16 v[14:17], v[194:197], v[208:211], v[14:17]
	v_mfma_f32_16x16x32_bf16 v[42:45], v[186:189], v[226:229], v[42:45]
	v_mfma_f32_16x16x32_bf16 v[10:13], v[194:197], v[226:229], v[10:13]
	v_mfma_f32_16x16x32_bf16 v[26:29], v[186:189], v[234:237], v[26:29]
	v_mfma_f32_16x16x32_bf16 v[6:9], v[194:197], v[234:237], v[6:9]
	v_mfma_f32_16x16x32_bf16 v[18:21], v[186:189], v[242:245], v[18:21]
	v_mfma_f32_16x16x32_bf16 v[2:5], v[194:197], v[242:245], v[2:5]
	v_mfma_f32_16x16x32_bf16 v[50:53], v[190:193], v[218:221], v[50:53]
	v_mfma_f32_16x16x32_bf16 v[14:17], v[198:201], v[218:221], v[14:17]
	v_mfma_f32_16x16x32_bf16 v[42:45], v[190:193], v[230:233], v[42:45]
	v_mfma_f32_16x16x32_bf16 v[10:13], v[198:201], v[230:233], v[10:13]
	v_mfma_f32_16x16x32_bf16 v[26:29], v[190:193], v[238:241], v[26:29]
	v_mfma_f32_16x16x32_bf16 v[6:9], v[198:201], v[238:241], v[6:9]
	v_mfma_f32_16x16x32_bf16 v[18:21], v[190:193], v[246:249], v[18:21]
	v_mfma_f32_16x16x32_bf16 v[2:5], v[198:201], v[246:249], v[2:5]
	s_setprio 0
	s_barrier
	s_add_i32 s44, s44, 2
	s_add_u32 s42, s42, 0x100
	s_addc_u32 s43, s43, 0
	s_cmp_gt_u32 s44, 13
	s_mov_b64 s[16:17], s[18:19]

;     __device__ __forceinline__ long arow(int pm) const { return (long)pm * BM; }
;     __device__ __forceinline__ long arow(int pm) const { if (pm < 132) { const int b = pm / 33, i = pm - b * 33; return (long)b * 8192 + 254 * i - 1; } return 32768 + (long)(pm - 132) * 256; }
;     __device__ __forceinline__ bool next(int i, Unit& u) const { if (i > 0) return false; u.pm = pm; u.pn = pn; return true; }
;     __device__ __forceinline__ long arow(int p) const { return (long)p * BM; }
; #define PG8_LDA(dst, b, h) do { _Pragma("unroll") for (int m = 0; m < 4; ++m) _Pragma("unroll") for (int k = 0; k < 2; ++k) dst[m][k] = *(const PG8_LAS bf16x8*)(lds + PG8_SA(b, h) + aoff + m * 2048 + k * 1024); } while (0)
; template <class Epi, class Sched, bool ALIGN_EPI = false, bool SP2 = false>
; __device__ __forceinline__ void gemm_phase(PG8_LAS unsigned char* lds, const Gemm g, const Sched& S, const Epi& E) {
;     ...
;         const bool has_next = S.next(ui + 1, nxt);
;         const char* nA = has_next ? (const char*)g.A + S.arow(nxt.pm) * rowb : cA; const char* nB = has_next ? (const char*)g.Bt + (size_t)nxt.pn * tstep : cB;
;         for (int t = 0; t < nt; t += 2) {
;             const bool last = (t == nt - 2);
;             const char* a1 = cA + (size_t)(t + 1) * kstep;
;             const char* a2 = last ? nA : cA + (size_t)(t + 2) * kstep; const char* b2 = last ? nB : cB + (size_t)(t + 2) * kstep;
;             const char* a3 = a2 + kstep; const char* b3 = b2 + kstep;
;             if (last && has_next) S.a_ready(nxt);
;             if constexpr (SP2) {
;             PG8_LDB(B0, 0, 0); PG8_LDB(B1, 0, 1); PG8_SCHED; PG8_LDA(At, 0, 0); PG8_STAGE(PG8_SA(1, 1), a1 + hstep, voffA);
;             PG8_WAIT_V(8); PG8_WAIT_L(0); PG8_BAR; PG8_MMA(0, 0, At, B0); PG8_MMA(0, 1, At, B1); PG8_BAR; PG8_SCHED;
;             PG8_LDA(At, 0, 1); PG8_STAGE(PG8_SB(0, 0), b2, voffB); PG8_STAGE(PG8_SB(0, 1), b2 + hstep, voffB); PG8_STAGE(PG8_SA(0, 0), a2, voffA);
;             PG8_WAIT_V(8); PG8_WAIT_L(0); PG8_BAR; PG8_MMA(1, 0, At, B0); PG8_MMA(1, 1, At, B1); PG8_BAR; PG8_SCHED;
;     ...
;         for (int a = 0; a < 2; ++a)
; #pragma unroll
;             for (int b = 0; b < 2; ++b)
; #pragma unroll
;                 for (int m = 0; m < 4; ++m)
; #pragma unroll
;                     for (int n = 0; n < 2; ++n) acc[a][b][m][n] = (f32x4){0.f, 0.f, 0.f, 0.f};
.LBB0_696:
	s_ashr_i32 s93, s92, 31
	s_lshl_b64 s[14:15], s[92:93], 19
	v_readlane_b32 s3, v255, 9
	s_add_u32 s96, s3, s14
	v_readlane_b32 s3, v255, 11
	s_addc_u32 s97, s3, s15
	s_and_b64 s[0:1], s[0:1], exec
	s_cselect_b32 s3, s97, s11
	s_cselect_b32 s14, s96, s10
	s_add_u32 s0, s12, 0x40080
	s_addc_u32 s1, s13, 0
	s_add_u32 s15, s10, 0x100
	s_addc_u32 s16, s11, 0
	s_mov_b32 s17, -2
	s_waitcnt vmcnt(0)
	s_add_u32 s10, s0, 0xfffc0080
	s_addc_u32 s11, s1, -1
	s_add_i32 s19, 0, 0x10000
	s_cmp_eq_u32 s17, 12
	s_cselect_b32 s13, s95, s11
	s_cselect_b32 s12, s94, s10
	v_add_u32_e32 v38, s19, v228
	s_cselect_b32 s11, s3, s16
	s_cselect_b32 s10, s14, s15
	s_add_i32 s22, 0, 0x14000
	ds_read_b128 v[106:109], v38
	ds_read_b128 v[110:113], v38 offset:1024
	ds_read_b128 v[114:117], v38 offset:2048
	ds_read_b128 v[118:121], v38 offset:3072
	v_add_u32_e32 v38, s22, v228
	ds_read_b128 v[122:125], v38
	ds_read_b128 v[126:129], v38 offset:1024
	ds_read_b128 v[130:133], v38 offset:2048
	ds_read_b128 v[134:137], v38 offset:3072
	v_lshl_add_u64 v[202:203], s[0:1], 0, v[190:191]
	s_add_i32 m0, s80, 0xc000
	ds_read_b128 v[170:173], v242
	ds_read_b128 v[174:177], v242 offset:1024
	ds_read_b128 v[178:181], v242 offset:2048
	ds_read_b128 v[194:197], v242 offset:3072
	ds_read_b128 v[198:201], v242 offset:4096
	ds_read_b128 v[208:211], v242 offset:5120
	ds_read_b128 v[218:221], v242 offset:6144
	ds_read_b128 v[244:247], v242 offset:7168
	global_load_lds_dwordx4 v[202:203], off
	v_lshl_add_u64 v[202:203], s[0:1], 0, v[192:193]
	s_add_i32 m0, s80, 0xe000
	s_nop 0
	global_load_lds_dwordx4 v[202:203], off
	s_waitcnt vmcnt(8)
	s_waitcnt lgkmcnt(0)
	s_barrier
	s_setprio 1
	s_waitcnt lgkmcnt(0)
	v_mfma_f32_16x16x32_bf16 v[166:169], v[106:109], v[170:173], 0
	v_mfma_f32_16x16x32_bf16 v[70:73], v[114:117], v[170:173], 0
	v_mfma_f32_16x16x32_bf16 v[158:161], v[106:109], v[178:181], 0
	v_mfma_f32_16x16x32_bf16 v[62:65], v[114:117], v[178:181], 0
	v_mfma_f32_16x16x32_bf16 v[150:153], v[106:109], v[198:201], 0
	v_mfma_f32_16x16x32_bf16 v[54:57], v[114:117], v[198:201], 0
	v_mfma_f32_16x16x32_bf16 v[142:145], v[106:109], v[218:221], 0
	v_mfma_f32_16x16x32_bf16 v[46:49], v[114:117], v[218:221], 0
	v_mfma_f32_16x16x32_bf16 v[166:169], v[110:113], v[174:177], v[166:169]
	v_mfma_f32_16x16x32_bf16 v[70:73], v[118:121], v[174:177], v[70:73]
	v_mfma_f32_16x16x32_bf16 v[158:161], v[110:113], v[194:197], v[158:161]
	v_mfma_f32_16x16x32_bf16 v[62:65], v[118:121], v[194:197], v[62:65]
	v_mfma_f32_16x16x32_bf16 v[150:153], v[110:113], v[208:211], v[150:153]
	v_mfma_f32_16x16x32_bf16 v[54:57], v[118:121], v[208:211], v[54:57]
	v_mfma_f32_16x16x32_bf16 v[142:145], v[110:113], v[244:247], v[142:145]
	v_mfma_f32_16x16x32_bf16 v[46:49], v[118:121], v[244:247], v[46:49]
	s_setprio 0
	s_setprio 1
	v_mfma_f32_16x16x32_bf16 v[162:165], v[122:125], v[170:173], 0
	v_mfma_f32_16x16x32_bf16 v[66:69], v[130:133], v[170:173], 0
	v_mfma_f32_16x16x32_bf16 v[154:157], v[122:125], v[178:181], 0
	v_mfma_f32_16x16x32_bf16 v[58:61], v[130:133], v[178:181], 0
	v_mfma_f32_16x16x32_bf16 v[146:149], v[122:125], v[198:201], 0
	v_mfma_f32_16x16x32_bf16 v[50:53], v[130:133], v[198:201], 0
	v_mfma_f32_16x16x32_bf16 v[138:141], v[122:125], v[218:221], 0
	v_mfma_f32_16x16x32_bf16 v[42:45], v[130:133], v[218:221], 0
	v_mfma_f32_16x16x32_bf16 v[162:165], v[126:129], v[174:177], v[162:165]
	v_mfma_f32_16x16x32_bf16 v[66:69], v[134:137], v[174:177], v[66:69]
	v_mfma_f32_16x16x32_bf16 v[154:157], v[126:129], v[194:197], v[154:157]
	v_mfma_f32_16x16x32_bf16 v[58:61], v[134:137], v[194:197], v[58:61]
	v_mfma_f32_16x16x32_bf16 v[146:149], v[126:129], v[208:211], v[146:149]
	v_mfma_f32_16x16x32_bf16 v[50:53], v[134:137], v[208:211], v[50:53]
	v_mfma_f32_16x16x32_bf16 v[138:141], v[126:129], v[244:247], v[138:141]
	v_mfma_f32_16x16x32_bf16 v[42:45], v[134:137], v[244:247], v[42:45]
	s_setprio 0
	s_barrier
	s_add_i32 s19, s19, s59
	v_lshl_add_u64 v[202:203], s[10:11], 0, v[34:35]
	s_mov_b32 m0, s19
	ds_read_b128 v[170:173], v242 offset:16384
	ds_read_b128 v[174:177], v242 offset:17408
	ds_read_b128 v[178:181], v242 offset:18432
	ds_read_b128 v[194:197], v242 offset:19456
	ds_read_b128 v[198:201], v242 offset:20480
	ds_read_b128 v[208:211], v242 offset:21504
	ds_read_b128 v[218:221], v242 offset:22528
	ds_read_b128 v[244:247], v242 offset:23552
	global_load_lds_dwordx4 v[202:203], off
	s_add_i32 m0, s19, 0x2000
	s_add_u32 s20, s10, 0x40000
	v_lshl_add_u64 v[212:213], s[10:11], 0, v[188:189]
	s_addc_u32 s21, s11, 0
	s_add_i32 s19, s22, s59
	global_load_lds_dwordx4 v[212:213], off
	v_lshl_add_u64 v[248:249], s[20:21], 0, v[34:35]
	s_mov_b32 m0, s19
	v_lshl_add_u64 v[250:251], s[12:13], 0, v[186:187]
	global_load_lds_dwordx4 v[248:249], off
	v_lshl_add_u64 v[248:249], s[20:21], 0, v[188:189]
	s_add_i32 m0, s19, 0x2000
	s_nop 0
	global_load_lds_dwordx4 v[248:249], off
	v_lshl_add_u64 v[248:249], s[12:13], 0, v[36:37]
	s_mov_b32 m0, s80
	s_nop 0
	global_load_lds_dwordx4 v[248:249], off
	s_mov_b32 m0, s81
	s_nop 0
	global_load_lds_dwordx4 v[250:251], off
	s_waitcnt vmcnt(8)
	s_waitcnt lgkmcnt(0)
	s_barrier
; #define PG8_STAGE(bufoff, gbase, voff) do { _Pragma("unroll") for (int _i = 0; _i < 2; ++_i) \
;         __builtin_amdgcn_global_load_lds((const unsigned*)((const char*)(gbase) + (voff)[_i]), (PG8_LAS unsigned*)(lds + (bufoff) + ldsw + _i * 8192), 16, 0, 0); } while (0)
; #define PG8_LDA(dst, b, h) do { _Pragma("unroll") for (int m = 0; m < 4; ++m) _Pragma("unroll") for (int k = 0; k < 2; ++k) dst[m][k] = *(const PG8_LAS bf16x8*)(lds + PG8_SA(b, h) + aoff + m * 2048 + k * 1024); } while (0)
; #define PG8_LDB(dst, b, h) do { _Pragma("unroll") for (int n = 0; n < 2; ++n) _Pragma("unroll") for (int k = 0; k < 2; ++k) dst[n][k] = *(const PG8_LAS bf16x8*)(lds + PG8_SB(b, h) + boff + n * 2048 + k * 1024); } while (0)
; #define PG8_MMA(ai, bj, At, Bt) do { __builtin_amdgcn_s_setprio(1); _Pragma("unroll") for (int m = 0; m < 4; ++m) _Pragma("unroll") for (int n = 0; n < 2; ++n) _Pragma("unroll") for (int k = 0; k < 2; ++k) \
;         acc[ai][bj][m][n] = __builtin_amdgcn_mfma_f32_16x16x32_bf16(Bt[n][k], At[m][k], acc[ai][bj][m][n], 0, 0, 0); __builtin_amdgcn_s_setprio(0); } while (0)
; #define PG8_WAIT_V(n) asm volatile("s_waitcnt vmcnt(" #n ")" ::: "memory")
; #define PG8_WAIT_L(n) asm volatile("s_waitcnt lgkmcnt(" #n ")" ::: "memory")
; #define PG8_BAR __builtin_amdgcn_s_barrier()
; #define PG8_SCHED __builtin_amdgcn_sched_barrier(0)
; template <class Epi, class Sched, bool ALIGN_EPI = false, bool SP2 = false>
; __device__ __forceinline__ void gemm_phase(PG8_LAS unsigned char* lds, const Gemm g, const Sched& S, const Epi& E) {
;     ...
;             PG8_WAIT_V(8); PG8_WAIT_L(0); PG8_BAR; PG8_MMA(1, 0, At, B0); PG8_MMA(1, 1, At, B1); PG8_BAR; PG8_SCHED;
;             PG8_LDB(B0, 1, 0); PG8_LDB(B1, 1, 1); PG8_SCHED; PG8_LDA(At, 1, 0); PG8_STAGE(PG8_SA(0, 1), a2 + hstep, voffA);
;             PG8_WAIT_V(8); PG8_WAIT_L(0); PG8_BAR; PG8_MMA(0, 0, At, B0); PG8_MMA(0, 1, At, B1); PG8_BAR; PG8_SCHED;
;             PG8_LDA(At, 1, 1); PG8_STAGE(PG8_SB(1, 0), b3, voffB); PG8_STAGE(PG8_SB(1, 1), b3 + hstep, voffB); PG8_STAGE(PG8_SA(1, 0), a3, voffA);
	s_setprio 1
	s_waitcnt lgkmcnt(0)
	v_mfma_f32_16x16x32_bf16 v[102:105], v[106:109], v[170:173], 0
	v_mfma_f32_16x16x32_bf16 v[30:33], v[114:117], v[170:173], 0
	v_mfma_f32_16x16x32_bf16 v[94:97], v[106:109], v[178:181], 0
	v_mfma_f32_16x16x32_bf16 v[22:25], v[114:117], v[178:181], 0
	v_mfma_f32_16x16x32_bf16 v[86:89], v[106:109], v[198:201], 0
	v_mfma_f32_16x16x32_bf16 v[14:17], v[114:117], v[198:201], 0
	v_mfma_f32_16x16x32_bf16 v[78:81], v[106:109], v[218:221], 0
	v_mfma_f32_16x16x32_bf16 v[6:9], v[114:117], v[218:221], 0
	v_mfma_f32_16x16x32_bf16 v[102:105], v[110:113], v[174:177], v[102:105]
	v_mfma_f32_16x16x32_bf16 v[30:33], v[118:121], v[174:177], v[30:33]
	v_mfma_f32_16x16x32_bf16 v[94:97], v[110:113], v[194:197], v[94:97]
	v_mfma_f32_16x16x32_bf16 v[22:25], v[118:121], v[194:197], v[22:25]
	v_mfma_f32_16x16x32_bf16 v[86:89], v[110:113], v[208:211], v[86:89]
	v_mfma_f32_16x16x32_bf16 v[14:17], v[118:121], v[208:211], v[14:17]
	v_mfma_f32_16x16x32_bf16 v[78:81], v[110:113], v[244:247], v[78:81]
	v_mfma_f32_16x16x32_bf16 v[6:9], v[118:121], v[244:247], v[6:9]
	s_setprio 0
	s_setprio 1
	v_mfma_f32_16x16x32_bf16 v[98:101], v[122:125], v[170:173], 0
	v_mfma_f32_16x16x32_bf16 v[26:29], v[130:133], v[170:173], 0
	v_mfma_f32_16x16x32_bf16 v[90:93], v[122:125], v[178:181], 0
	v_mfma_f32_16x16x32_bf16 v[18:21], v[130:133], v[178:181], 0
	v_mfma_f32_16x16x32_bf16 v[82:85], v[122:125], v[198:201], 0
	v_mfma_f32_16x16x32_bf16 v[10:13], v[130:133], v[198:201], 0
	v_mfma_f32_16x16x32_bf16 v[74:77], v[122:125], v[218:221], 0
	v_mfma_f32_16x16x32_bf16 v[2:5], v[130:133], v[218:221], 0
	v_mfma_f32_16x16x32_bf16 v[98:101], v[126:129], v[174:177], v[98:101]
	v_mfma_f32_16x16x32_bf16 v[26:29], v[134:137], v[174:177], v[26:29]
	v_mfma_f32_16x16x32_bf16 v[90:93], v[126:129], v[194:197], v[90:93]
	v_mfma_f32_16x16x32_bf16 v[18:21], v[134:137], v[194:197], v[18:21]
	v_mfma_f32_16x16x32_bf16 v[82:85], v[126:129], v[208:211], v[82:85]
	v_mfma_f32_16x16x32_bf16 v[10:13], v[134:137], v[208:211], v[10:13]
	v_mfma_f32_16x16x32_bf16 v[74:77], v[126:129], v[244:247], v[74:77]
	v_mfma_f32_16x16x32_bf16 v[2:5], v[134:137], v[244:247], v[2:5]
	s_setprio 0
	s_barrier
	s_add_i32 s19, 0, 0x18000
	v_add_u32_e32 v38, s19, v228
	s_add_i32 s20, 0, 0x1c000
	ds_read_b128 v[106:109], v38
	ds_read_b128 v[110:113], v38 offset:1024
	ds_read_b128 v[114:117], v38 offset:2048
	ds_read_b128 v[118:121], v38 offset:3072
	v_add_u32_e32 v38, s20, v228
	ds_read_b128 v[122:125], v38
	ds_read_b128 v[126:129], v38 offset:1024
	ds_read_b128 v[130:133], v38 offset:2048
	ds_read_b128 v[134:137], v38 offset:3072
	s_add_u32 s12, s12, 0x40000
	s_addc_u32 s13, s13, 0
	s_mov_b32 m0, s76
	v_lshl_add_u64 v[38:39], s[12:13], 0, v[36:37]
	ds_read_b128 v[170:173], v242 offset:32768
	ds_read_b128 v[174:177], v242 offset:33792
	ds_read_b128 v[178:181], v242 offset:34816
	ds_read_b128 v[194:197], v242 offset:35840
	ds_read_b128 v[198:201], v242 offset:36864
	ds_read_b128 v[208:211], v242 offset:37888
	ds_read_b128 v[218:221], v242 offset:38912
	ds_read_b128 v[244:247], v242 offset:39936
	global_load_lds_dwordx4 v[38:39], off
	v_lshl_add_u64 v[38:39], s[12:13], 0, v[186:187]
	s_mov_b32 m0, s77
	s_nop 0
	global_load_lds_dwordx4 v[38:39], off
	s_waitcnt vmcnt(8)
	s_waitcnt lgkmcnt(0)
	s_barrier
	s_setprio 1
	s_waitcnt lgkmcnt(0)
	v_mfma_f32_16x16x32_bf16 v[166:169], v[106:109], v[170:173], v[166:169]
	v_mfma_f32_16x16x32_bf16 v[70:73], v[114:117], v[170:173], v[70:73]
	v_mfma_f32_16x16x32_bf16 v[158:161], v[106:109], v[178:181], v[158:161]
	v_mfma_f32_16x16x32_bf16 v[62:65], v[114:117], v[178:181], v[62:65]
	v_mfma_f32_16x16x32_bf16 v[150:153], v[106:109], v[198:201], v[150:153]
	v_mfma_f32_16x16x32_bf16 v[54:57], v[114:117], v[198:201], v[54:57]
	v_mfma_f32_16x16x32_bf16 v[142:145], v[106:109], v[218:221], v[142:145]
	v_mfma_f32_16x16x32_bf16 v[46:49], v[114:117], v[218:221], v[46:49]
	v_mfma_f32_16x16x32_bf16 v[166:169], v[110:113], v[174:177], v[166:169]
	v_mfma_f32_16x16x32_bf16 v[70:73], v[118:121], v[174:177], v[70:73]
	v_mfma_f32_16x16x32_bf16 v[158:161], v[110:113], v[194:197], v[158:161]
	v_mfma_f32_16x16x32_bf16 v[62:65], v[118:121], v[194:197], v[62:65]
	v_mfma_f32_16x16x32_bf16 v[150:153], v[110:113], v[208:211], v[150:153]
	v_mfma_f32_16x16x32_bf16 v[54:57], v[118:121], v[208:211], v[54:57]
	v_mfma_f32_16x16x32_bf16 v[142:145], v[110:113], v[244:247], v[142:145]
	v_mfma_f32_16x16x32_bf16 v[46:49], v[118:121], v[244:247], v[46:49]
	s_setprio 0
	s_setprio 1
	v_mfma_f32_16x16x32_bf16 v[162:165], v[122:125], v[170:173], v[162:165]
	v_mfma_f32_16x16x32_bf16 v[66:69], v[130:133], v[170:173], v[66:69]
	v_mfma_f32_16x16x32_bf16 v[154:157], v[122:125], v[178:181], v[154:157]
	v_mfma_f32_16x16x32_bf16 v[58:61], v[130:133], v[178:181], v[58:61]
	v_mfma_f32_16x16x32_bf16 v[146:149], v[122:125], v[198:201], v[146:149]
	v_mfma_f32_16x16x32_bf16 v[50:53], v[130:133], v[198:201], v[50:53]
	v_mfma_f32_16x16x32_bf16 v[138:141], v[122:125], v[218:221], v[138:141]
	v_mfma_f32_16x16x32_bf16 v[42:45], v[130:133], v[218:221], v[42:45]
	v_mfma_f32_16x16x32_bf16 v[162:165], v[126:129], v[174:177], v[162:165]
	v_mfma_f32_16x16x32_bf16 v[66:69], v[134:137], v[174:177], v[66:69]
	v_mfma_f32_16x16x32_bf16 v[154:157], v[126:129], v[194:197], v[154:157]
	v_mfma_f32_16x16x32_bf16 v[58:61], v[134:137], v[194:197], v[58:61]
	v_mfma_f32_16x16x32_bf16 v[146:149], v[126:129], v[208:211], v[146:149]
	v_mfma_f32_16x16x32_bf16 v[50:53], v[134:137], v[208:211], v[50:53]
	v_mfma_f32_16x16x32_bf16 v[138:141], v[126:129], v[244:247], v[138:141]
	v_mfma_f32_16x16x32_bf16 v[42:45], v[134:137], v[244:247], v[42:45]
	s_setprio 0
	s_barrier
; #define PG8_STAGE(bufoff, gbase, voff) do { _Pragma("unroll") for (int _i = 0; _i < 2; ++_i) \
;         __builtin_amdgcn_global_load_lds((const unsigned*)((const char*)(gbase) + (voff)[_i]), (PG8_LAS unsigned*)(lds + (bufoff) + ldsw + _i * 8192), 16, 0, 0); } while (0)
; #define PG8_LDA(dst, b, h) do { _Pragma("unroll") for (int m = 0; m < 4; ++m) _Pragma("unroll") for (int k = 0; k < 2; ++k) dst[m][k] = *(const PG8_LAS bf16x8*)(lds + PG8_SA(b, h) + aoff + m * 2048 + k * 1024); } while (0)
; #define PG8_MMA(ai, bj, At, Bt) do { __builtin_amdgcn_s_setprio(1); _Pragma("unroll") for (int m = 0; m < 4; ++m) _Pragma("unroll") for (int n = 0; n < 2; ++n) _Pragma("unroll") for (int k = 0; k < 2; ++k) \
;         acc[ai][bj][m][n] = __builtin_amdgcn_mfma_f32_16x16x32_bf16(Bt[n][k], At[m][k], acc[ai][bj][m][n], 0, 0, 0); __builtin_amdgcn_s_setprio(0); } while (0)
; #define PG8_WAIT_V(n) asm volatile("s_waitcnt vmcnt(" #n ")" ::: "memory")
; #define PG8_WAIT_L(n) asm volatile("s_waitcnt lgkmcnt(" #n ")" ::: "memory")
; #define PG8_BAR __builtin_amdgcn_s_barrier()
; #define PG8_SCHED __builtin_amdgcn_sched_barrier(0)
; template <class Epi, class Sched, bool ALIGN_EPI = false, bool SP2 = false>
; __device__ __forceinline__ void gemm_phase(PG8_LAS unsigned char* lds, const Gemm g, const Sched& S, const Epi& E) {
;     ...
;             PG8_LDA(At, 1, 1); PG8_STAGE(PG8_SB(1, 0), b3, voffB); PG8_STAGE(PG8_SB(1, 1), b3 + hstep, voffB); PG8_STAGE(PG8_SA(1, 0), a3, voffA);
;             PG8_WAIT_V(8); PG8_WAIT_L(0); PG8_BAR; PG8_MMA(1, 0, At, B0); PG8_MMA(1, 1, At, B1); PG8_BAR; PG8_SCHED;
	s_add_i32 s12, s19, s59
	v_lshl_add_u64 v[38:39], v[202:203], 0, s[70:71]
	s_mov_b32 m0, s12
	ds_read_b128 v[170:173], v242 offset:49152
	ds_read_b128 v[174:177], v242 offset:50176
	ds_read_b128 v[178:181], v242 offset:51200
	ds_read_b128 v[194:197], v242 offset:52224
	ds_read_b128 v[198:201], v242 offset:53248
	ds_read_b128 v[208:211], v242 offset:54272
	ds_read_b128 v[218:221], v242 offset:55296
	ds_read_b128 v[244:247], v242 offset:56320
	global_load_lds_dwordx4 v[38:39], off
	s_add_i32 m0, s12, 0x2000
	s_add_u32 s10, s10, 0x40080
	v_lshl_add_u64 v[38:39], v[212:213], 0, s[70:71]
	s_addc_u32 s11, s11, 0
	s_add_i32 s12, s20, s59
	global_load_lds_dwordx4 v[38:39], off
	v_lshl_add_u64 v[38:39], s[10:11], 0, v[34:35]
	s_mov_b32 m0, s12
	s_nop 0
	global_load_lds_dwordx4 v[38:39], off
	v_lshl_add_u64 v[38:39], s[10:11], 0, v[188:189]
	s_add_i32 m0, s12, 0x2000
	s_nop 0
	global_load_lds_dwordx4 v[38:39], off
	v_lshl_add_u64 v[38:39], v[248:249], 0, s[70:71]
	s_mov_b32 m0, s82
	s_nop 0
	global_load_lds_dwordx4 v[38:39], off
	v_lshl_add_u64 v[38:39], v[250:251], 0, s[70:71]
	s_mov_b32 m0, s83
	s_nop 0
	global_load_lds_dwordx4 v[38:39], off
	s_waitcnt vmcnt(8)
	s_waitcnt lgkmcnt(0)
	s_barrier
	s_setprio 1
	s_waitcnt lgkmcnt(0)
	v_mfma_f32_16x16x32_bf16 v[102:105], v[106:109], v[170:173], v[102:105]
	v_mfma_f32_16x16x32_bf16 v[30:33], v[114:117], v[170:173], v[30:33]
	v_mfma_f32_16x16x32_bf16 v[94:97], v[106:109], v[178:181], v[94:97]
	v_mfma_f32_16x16x32_bf16 v[22:25], v[114:117], v[178:181], v[22:25]
	v_mfma_f32_16x16x32_bf16 v[86:89], v[106:109], v[198:201], v[86:89]
	v_mfma_f32_16x16x32_bf16 v[14:17], v[114:117], v[198:201], v[14:17]
	v_mfma_f32_16x16x32_bf16 v[78:81], v[106:109], v[218:221], v[78:81]
	v_mfma_f32_16x16x32_bf16 v[6:9], v[114:117], v[218:221], v[6:9]
	v_mfma_f32_16x16x32_bf16 v[102:105], v[110:113], v[174:177], v[102:105]
	v_mfma_f32_16x16x32_bf16 v[30:33], v[118:121], v[174:177], v[30:33]
	v_mfma_f32_16x16x32_bf16 v[94:97], v[110:113], v[194:197], v[94:97]
	v_mfma_f32_16x16x32_bf16 v[22:25], v[118:121], v[194:197], v[22:25]
	v_mfma_f32_16x16x32_bf16 v[86:89], v[110:113], v[208:211], v[86:89]
	v_mfma_f32_16x16x32_bf16 v[14:17], v[118:121], v[208:211], v[14:17]
	v_mfma_f32_16x16x32_bf16 v[78:81], v[110:113], v[244:247], v[78:81]
	v_mfma_f32_16x16x32_bf16 v[6:9], v[118:121], v[244:247], v[6:9]
	s_setprio 0
	s_setprio 1
	v_mfma_f32_16x16x32_bf16 v[98:101], v[122:125], v[170:173], v[98:101]
	v_mfma_f32_16x16x32_bf16 v[26:29], v[130:133], v[170:173], v[26:29]
	v_mfma_f32_16x16x32_bf16 v[90:93], v[122:125], v[178:181], v[90:93]
	v_mfma_f32_16x16x32_bf16 v[18:21], v[130:133], v[178:181], v[18:21]
	v_mfma_f32_16x16x32_bf16 v[82:85], v[122:125], v[198:201], v[82:85]
	v_mfma_f32_16x16x32_bf16 v[10:13], v[130:133], v[198:201], v[10:13]
	v_mfma_f32_16x16x32_bf16 v[74:77], v[122:125], v[218:221], v[74:77]
	v_mfma_f32_16x16x32_bf16 v[2:5], v[130:133], v[218:221], v[2:5]
	v_mfma_f32_16x16x32_bf16 v[98:101], v[126:129], v[174:177], v[98:101]
	v_mfma_f32_16x16x32_bf16 v[26:29], v[134:137], v[174:177], v[26:29]
	v_mfma_f32_16x16x32_bf16 v[90:93], v[126:129], v[194:197], v[90:93]
	v_mfma_f32_16x16x32_bf16 v[18:21], v[134:137], v[194:197], v[18:21]
	v_mfma_f32_16x16x32_bf16 v[82:85], v[126:129], v[208:211], v[82:85]
	v_mfma_f32_16x16x32_bf16 v[10:13], v[134:137], v[208:211], v[10:13]
	v_mfma_f32_16x16x32_bf16 v[74:77], v[126:129], v[244:247], v[74:77]
	v_mfma_f32_16x16x32_bf16 v[2:5], v[134:137], v[244:247], v[2:5]
	s_setprio 0
	s_barrier
	s_add_i32 s17, s17, 2
	s_add_u32 s0, s0, 0x100
	s_addc_u32 s1, s1, 0
	s_add_u32 s15, s15, 0x100
	s_addc_u32 s16, s16, 0
	s_cmp_gt_u32 s17, 13

;     __device__ __forceinline__ long arow(int pm) const { return (long)pm * BM; }
;     __device__ __forceinline__ long arow(int pm) const { if (pm < 132) { const int b = pm / 33, i = pm - b * 33; return (long)b * 8192 + 254 * i - 1; } return 32768 + (long)(pm - 132) * 256; }
;     __device__ __forceinline__ bool next(int i, Unit& u) const { if (i > 0) return false; u.pm = pm; u.pn = pn; return true; }
;     __device__ __forceinline__ long arow(int p) const { return (long)p * BM; }
; #define PG8_LDA(dst, b, h) do { _Pragma("unroll") for (int m = 0; m < 4; ++m) _Pragma("unroll") for (int k = 0; k < 2; ++k) dst[m][k] = *(const PG8_LAS bf16x8*)(lds + PG8_SA(b, h) + aoff + m * 2048 + k * 1024); } while (0)
; template <class Epi, class Sched, bool ALIGN_EPI = false, bool SP2 = false>
; __device__ __forceinline__ void gemm_phase(PG8_LAS unsigned char* lds, const Gemm g, const Sched& S, const Epi& E) {
;     ...
;         const bool has_next = S.next(ui + 1, nxt);
;         const char* nA = has_next ? (const char*)g.A + S.arow(nxt.pm) * rowb : cA; const char* nB = has_next ? (const char*)g.Bt + (size_t)nxt.pn * tstep : cB;
;         for (int t = 0; t < nt; t += 2) {
;             const bool last = (t == nt - 2);
;             const char* a1 = cA + (size_t)(t + 1) * kstep;
;             const char* a2 = last ? nA : cA + (size_t)(t + 2) * kstep; const char* b2 = last ? nB : cB + (size_t)(t + 2) * kstep;
;             const char* a3 = a2 + kstep; const char* b3 = b2 + kstep;
;             if (last && has_next) S.a_ready(nxt);
;             if constexpr (SP2) {
;             PG8_LDB(B0, 0, 0); PG8_LDB(B1, 0, 1); PG8_SCHED; PG8_LDA(At, 0, 0); PG8_STAGE(PG8_SA(1, 1), a1 + hstep, voffA);
;             PG8_WAIT_V(8); PG8_WAIT_L(0); PG8_BAR; PG8_MMA(0, 0, At, B0); PG8_MMA(0, 1, At, B1); PG8_BAR; PG8_SCHED;
;             PG8_LDA(At, 0, 1); PG8_STAGE(PG8_SB(0, 0), b2, voffB); PG8_STAGE(PG8_SB(0, 1), b2 + hstep, voffB); PG8_STAGE(PG8_SA(0, 0), a2, voffA);
;             PG8_WAIT_V(8); PG8_WAIT_L(0); PG8_BAR; PG8_MMA(1, 0, At, B0); PG8_MMA(1, 1, At, B1); PG8_BAR; PG8_SCHED;
;     ...
;         for (int a = 0; a < 2; ++a)
; #pragma unroll
;             for (int b = 0; b < 2; ++b)
; #pragma unroll
;                 for (int m = 0; m < 4; ++m)
; #pragma unroll
;                     for (int n = 0; n < 2; ++n) acc[a][b][m][n] = (f32x4){0.f, 0.f, 0.f, 0.f};
.LBB0_989:
	s_add_u32 s11, s14, 0x100
	s_addc_u32 s41, s15, 0
	s_mov_b32 s42, -2
	s_waitcnt vmcnt(0)
	s_add_u32 s14, s12, 0x100
	s_addc_u32 s15, s13, 0
	s_add_i32 s43, 0, 0x10000
	s_cmp_eq_u32 s42, 40
	s_cselect_b32 s19, s1, s15
	s_cselect_b32 s18, s0, s14
	v_add_u32_e32 v38, s43, v168
	s_cselect_b32 s17, s9, s41
	s_cselect_b32 s16, s8, s11
	s_add_i32 s44, 0, 0x14000
	ds_read_b128 v[138:141], v38
	ds_read_b128 v[162:165], v38 offset:1024
	ds_read_b128 v[172:175], v38 offset:2048
	ds_read_b128 v[176:179], v38 offset:3072
	v_add_u32_e32 v38, s44, v168
	ds_read_b128 v[186:189], v38
	ds_read_b128 v[190:193], v38 offset:1024
	ds_read_b128 v[194:197], v38 offset:2048
	ds_read_b128 v[198:201], v38 offset:3072
	v_lshl_add_u64 v[166:167], s[12:13], 0, v[158:159]
	s_add_i32 m0, s27, 0xc000
	ds_read_b128 v[208:211], v170
	ds_read_b128 v[218:221], v170 offset:1024
	ds_read_b128 v[226:229], v170 offset:2048
	ds_read_b128 v[230:233], v170 offset:3072
	ds_read_b128 v[234:237], v170 offset:4096
	ds_read_b128 v[238:241], v170 offset:5120
	ds_read_b128 v[242:245], v170 offset:6144
	ds_read_b128 v[246:249], v170 offset:7168
	global_load_lds_dwordx4 v[166:167], off
	v_lshl_add_u64 v[166:167], s[12:13], 0, v[160:161]
	s_add_i32 m0, s27, 0xe000
	s_nop 0
	global_load_lds_dwordx4 v[166:167], off
	s_waitcnt vmcnt(8)
	s_waitcnt lgkmcnt(0)
	s_barrier
	s_setprio 1
	s_waitcnt lgkmcnt(0)
	v_mfma_f32_16x16x32_bf16 v[134:137], v[138:141], v[208:211], 0
	v_mfma_f32_16x16x32_bf16 v[106:109], v[172:175], v[208:211], 0
	v_mfma_f32_16x16x32_bf16 v[130:133], v[138:141], v[226:229], 0
	v_mfma_f32_16x16x32_bf16 v[102:105], v[172:175], v[226:229], 0
	v_mfma_f32_16x16x32_bf16 v[126:129], v[138:141], v[234:237], 0
	v_mfma_f32_16x16x32_bf16 v[98:101], v[172:175], v[234:237], 0
	v_mfma_f32_16x16x32_bf16 v[122:125], v[138:141], v[242:245], 0
	v_mfma_f32_16x16x32_bf16 v[90:93], v[172:175], v[242:245], 0
	v_mfma_f32_16x16x32_bf16 v[134:137], v[162:165], v[218:221], v[134:137]
	v_mfma_f32_16x16x32_bf16 v[106:109], v[176:179], v[218:221], v[106:109]
	v_mfma_f32_16x16x32_bf16 v[130:133], v[162:165], v[230:233], v[130:133]
	v_mfma_f32_16x16x32_bf16 v[102:105], v[176:179], v[230:233], v[102:105]
	v_mfma_f32_16x16x32_bf16 v[126:129], v[162:165], v[238:241], v[126:129]
	v_mfma_f32_16x16x32_bf16 v[98:101], v[176:179], v[238:241], v[98:101]
	v_mfma_f32_16x16x32_bf16 v[122:125], v[162:165], v[246:249], v[122:125]
	v_mfma_f32_16x16x32_bf16 v[90:93], v[176:179], v[246:249], v[90:93]
	s_setprio 0
	s_setprio 1
	v_mfma_f32_16x16x32_bf16 v[82:85], v[186:189], v[208:211], 0
	v_mfma_f32_16x16x32_bf16 v[54:57], v[194:197], v[208:211], 0
	v_mfma_f32_16x16x32_bf16 v[74:77], v[186:189], v[226:229], 0
	v_mfma_f32_16x16x32_bf16 v[46:49], v[194:197], v[226:229], 0
	v_mfma_f32_16x16x32_bf16 v[66:69], v[186:189], v[234:237], 0
	v_mfma_f32_16x16x32_bf16 v[30:33], v[194:197], v[234:237], 0
	v_mfma_f32_16x16x32_bf16 v[58:61], v[186:189], v[242:245], 0
	v_mfma_f32_16x16x32_bf16 v[22:25], v[194:197], v[242:245], 0
	v_mfma_f32_16x16x32_bf16 v[82:85], v[190:193], v[218:221], v[82:85]
	v_mfma_f32_16x16x32_bf16 v[54:57], v[198:201], v[218:221], v[54:57]
	v_mfma_f32_16x16x32_bf16 v[74:77], v[190:193], v[230:233], v[74:77]
	v_mfma_f32_16x16x32_bf16 v[46:49], v[198:201], v[230:233], v[46:49]
	v_mfma_f32_16x16x32_bf16 v[66:69], v[190:193], v[238:241], v[66:69]
	v_mfma_f32_16x16x32_bf16 v[30:33], v[198:201], v[238:241], v[30:33]
	v_mfma_f32_16x16x32_bf16 v[58:61], v[190:193], v[246:249], v[58:61]
	v_mfma_f32_16x16x32_bf16 v[22:25], v[198:201], v[246:249], v[22:25]
	s_setprio 0
	s_barrier
	s_add_i32 s12, s43, s26
	v_lshl_add_u64 v[166:167], s[16:17], 0, v[34:35]
	s_mov_b32 m0, s12
	ds_read_b128 v[208:211], v170 offset:16384
	ds_read_b128 v[218:221], v170 offset:17408
	ds_read_b128 v[226:229], v170 offset:18432
	ds_read_b128 v[230:233], v170 offset:19456
	ds_read_b128 v[234:237], v170 offset:20480
	ds_read_b128 v[238:241], v170 offset:21504
	ds_read_b128 v[242:245], v170 offset:22528
	ds_read_b128 v[246:249], v170 offset:23552
	global_load_lds_dwordx4 v[166:167], off
	s_add_i32 m0, s12, 0x2000
	s_add_u32 s12, s16, 0xb0000
	v_lshl_add_u64 v[180:181], s[16:17], 0, v[36:37]
	s_addc_u32 s13, s17, 0
	s_add_i32 s43, s44, s26
	global_load_lds_dwordx4 v[180:181], off
	v_lshl_add_u64 v[202:203], s[12:13], 0, v[34:35]
	s_mov_b32 m0, s43
	v_lshl_add_u64 v[212:213], s[18:19], 0, v[36:37]
	global_load_lds_dwordx4 v[202:203], off
	v_lshl_add_u64 v[202:203], s[12:13], 0, v[36:37]
	s_add_i32 m0, s43, 0x2000
	s_nop 0
	global_load_lds_dwordx4 v[202:203], off
	v_lshl_add_u64 v[202:203], s[18:19], 0, v[34:35]
	s_mov_b32 m0, s27
	s_nop 0
	global_load_lds_dwordx4 v[202:203], off
	s_mov_b32 m0, s28
	s_nop 0
	global_load_lds_dwordx4 v[212:213], off
	s_waitcnt vmcnt(8)
	s_waitcnt lgkmcnt(0)
	s_barrier
; #define PG8_STAGE(bufoff, gbase, voff) do { _Pragma("unroll") for (int _i = 0; _i < 2; ++_i) \
;         __builtin_amdgcn_global_load_lds((const unsigned*)((const char*)(gbase) + (voff)[_i]), (PG8_LAS unsigned*)(lds + (bufoff) + ldsw + _i * 8192), 16, 0, 0); } while (0)
; #define PG8_LDA(dst, b, h) do { _Pragma("unroll") for (int m = 0; m < 4; ++m) _Pragma("unroll") for (int k = 0; k < 2; ++k) dst[m][k] = *(const PG8_LAS bf16x8*)(lds + PG8_SA(b, h) + aoff + m * 2048 + k * 1024); } while (0)
; #define PG8_LDB(dst, b, h) do { _Pragma("unroll") for (int n = 0; n < 2; ++n) _Pragma("unroll") for (int k = 0; k < 2; ++k) dst[n][k] = *(const PG8_LAS bf16x8*)(lds + PG8_SB(b, h) + boff + n * 2048 + k * 1024); } while (0)
; #define PG8_MMA(ai, bj, At, Bt) do { __builtin_amdgcn_s_setprio(1); _Pragma("unroll") for (int m = 0; m < 4; ++m) _Pragma("unroll") for (int n = 0; n < 2; ++n) _Pragma("unroll") for (int k = 0; k < 2; ++k) \
;         acc[ai][bj][m][n] = __builtin_amdgcn_mfma_f32_16x16x32_bf16(Bt[n][k], At[m][k], acc[ai][bj][m][n], 0, 0, 0); __builtin_amdgcn_s_setprio(0); } while (0)
; #define PG8_WAIT_V(n) asm volatile("s_waitcnt vmcnt(" #n ")" ::: "memory")
; #define PG8_WAIT_L(n) asm volatile("s_waitcnt lgkmcnt(" #n ")" ::: "memory")
; #define PG8_BAR __builtin_amdgcn_s_barrier()
; #define PG8_SCHED __builtin_amdgcn_sched_barrier(0)
; template <class Epi, class Sched, bool ALIGN_EPI = false, bool SP2 = false>
; __device__ __forceinline__ void gemm_phase(PG8_LAS unsigned char* lds, const Gemm g, const Sched& S, const Epi& E) {
;     ...
;             PG8_WAIT_V(8); PG8_WAIT_L(0); PG8_BAR; PG8_MMA(1, 0, At, B0); PG8_MMA(1, 1, At, B1); PG8_BAR; PG8_SCHED;
;             PG8_LDB(B0, 1, 0); PG8_LDB(B1, 1, 1); PG8_SCHED; PG8_LDA(At, 1, 0); PG8_STAGE(PG8_SA(0, 1), a2 + hstep, voffA);
;             PG8_WAIT_V(8); PG8_WAIT_L(0); PG8_BAR; PG8_MMA(0, 0, At, B0); PG8_MMA(0, 1, At, B1); PG8_BAR; PG8_SCHED;
;             PG8_LDA(At, 1, 1); PG8_STAGE(PG8_SB(1, 0), b3, voffB); PG8_STAGE(PG8_SB(1, 1), b3 + hstep, voffB); PG8_STAGE(PG8_SA(1, 0), a3, voffA);
	s_setprio 1
	s_waitcnt lgkmcnt(0)
	v_mfma_f32_16x16x32_bf16 v[118:121], v[138:141], v[208:211], 0
	v_mfma_f32_16x16x32_bf16 v[86:89], v[172:175], v[208:211], 0
	v_mfma_f32_16x16x32_bf16 v[114:117], v[138:141], v[226:229], 0
	v_mfma_f32_16x16x32_bf16 v[78:81], v[172:175], v[226:229], 0
	v_mfma_f32_16x16x32_bf16 v[110:113], v[138:141], v[234:237], 0
	v_mfma_f32_16x16x32_bf16 v[70:73], v[172:175], v[234:237], 0
	v_mfma_f32_16x16x32_bf16 v[94:97], v[138:141], v[242:245], 0
	v_mfma_f32_16x16x32_bf16 v[62:65], v[172:175], v[242:245], 0
	v_mfma_f32_16x16x32_bf16 v[118:121], v[162:165], v[218:221], v[118:121]
	v_mfma_f32_16x16x32_bf16 v[86:89], v[176:179], v[218:221], v[86:89]
	v_mfma_f32_16x16x32_bf16 v[114:117], v[162:165], v[230:233], v[114:117]
	v_mfma_f32_16x16x32_bf16 v[78:81], v[176:179], v[230:233], v[78:81]
	v_mfma_f32_16x16x32_bf16 v[110:113], v[162:165], v[238:241], v[110:113]
	v_mfma_f32_16x16x32_bf16 v[70:73], v[176:179], v[238:241], v[70:73]
	v_mfma_f32_16x16x32_bf16 v[94:97], v[162:165], v[246:249], v[94:97]
	v_mfma_f32_16x16x32_bf16 v[62:65], v[176:179], v[246:249], v[62:65]
	s_setprio 0
	s_setprio 1
	v_mfma_f32_16x16x32_bf16 v[50:53], v[186:189], v[208:211], 0
	v_mfma_f32_16x16x32_bf16 v[14:17], v[194:197], v[208:211], 0
	v_mfma_f32_16x16x32_bf16 v[42:45], v[186:189], v[226:229], 0
	v_mfma_f32_16x16x32_bf16 v[10:13], v[194:197], v[226:229], 0
	v_mfma_f32_16x16x32_bf16 v[26:29], v[186:189], v[234:237], 0
	v_mfma_f32_16x16x32_bf16 v[6:9], v[194:197], v[234:237], 0
	v_mfma_f32_16x16x32_bf16 v[18:21], v[186:189], v[242:245], 0
	v_mfma_f32_16x16x32_bf16 v[2:5], v[194:197], v[242:245], 0
	v_mfma_f32_16x16x32_bf16 v[50:53], v[190:193], v[218:221], v[50:53]
	v_mfma_f32_16x16x32_bf16 v[14:17], v[198:201], v[218:221], v[14:17]
	v_mfma_f32_16x16x32_bf16 v[42:45], v[190:193], v[230:233], v[42:45]
	v_mfma_f32_16x16x32_bf16 v[10:13], v[198:201], v[230:233], v[10:13]
	v_mfma_f32_16x16x32_bf16 v[26:29], v[190:193], v[238:241], v[26:29]
	v_mfma_f32_16x16x32_bf16 v[6:9], v[198:201], v[238:241], v[6:9]
	v_mfma_f32_16x16x32_bf16 v[18:21], v[190:193], v[246:249], v[18:21]
	v_mfma_f32_16x16x32_bf16 v[2:5], v[198:201], v[246:249], v[2:5]
	s_setprio 0
	s_barrier
	s_add_i32 s43, 0, 0x18000
	v_add_u32_e32 v38, s43, v168
	s_add_i32 s44, 0, 0x1c000
	ds_read_b128 v[138:141], v38
	ds_read_b128 v[162:165], v38 offset:1024
	ds_read_b128 v[172:175], v38 offset:2048
	ds_read_b128 v[176:179], v38 offset:3072
	v_add_u32_e32 v38, s44, v168
	ds_read_b128 v[186:189], v38
	ds_read_b128 v[190:193], v38 offset:1024
	ds_read_b128 v[194:197], v38 offset:2048
	ds_read_b128 v[198:201], v38 offset:3072
	s_add_u32 s12, s18, 0xb0000
	s_addc_u32 s13, s19, 0
	s_mov_b32 m0, s29
	v_lshl_add_u64 v[250:251], s[12:13], 0, v[34:35]
	ds_read_b128 v[208:211], v170 offset:32768
	ds_read_b128 v[218:221], v170 offset:33792
	ds_read_b128 v[226:229], v170 offset:34816
	ds_read_b128 v[230:233], v170 offset:35840
	ds_read_b128 v[234:237], v170 offset:36864
	ds_read_b128 v[238:241], v170 offset:37888
	ds_read_b128 v[242:245], v170 offset:38912
	ds_read_b128 v[246:249], v170 offset:39936
	global_load_lds_dwordx4 v[250:251], off
	v_lshl_add_u64 v[250:251], s[12:13], 0, v[36:37]
	s_mov_b32 m0, s30
	s_nop 0
	global_load_lds_dwordx4 v[250:251], off
	s_waitcnt vmcnt(8)
	s_waitcnt lgkmcnt(0)
	s_barrier
	s_setprio 1
	s_waitcnt lgkmcnt(0)
	v_mfma_f32_16x16x32_bf16 v[134:137], v[138:141], v[208:211], v[134:137]
	v_mfma_f32_16x16x32_bf16 v[106:109], v[172:175], v[208:211], v[106:109]
	v_mfma_f32_16x16x32_bf16 v[130:133], v[138:141], v[226:229], v[130:133]
	v_mfma_f32_16x16x32_bf16 v[102:105], v[172:175], v[226:229], v[102:105]
	v_mfma_f32_16x16x32_bf16 v[126:129], v[138:141], v[234:237], v[126:129]
	v_mfma_f32_16x16x32_bf16 v[98:101], v[172:175], v[234:237], v[98:101]
	v_mfma_f32_16x16x32_bf16 v[122:125], v[138:141], v[242:245], v[122:125]
	v_mfma_f32_16x16x32_bf16 v[90:93], v[172:175], v[242:245], v[90:93]
	v_mfma_f32_16x16x32_bf16 v[134:137], v[162:165], v[218:221], v[134:137]
	v_mfma_f32_16x16x32_bf16 v[106:109], v[176:179], v[218:221], v[106:109]
	v_mfma_f32_16x16x32_bf16 v[130:133], v[162:165], v[230:233], v[130:133]
	v_mfma_f32_16x16x32_bf16 v[102:105], v[176:179], v[230:233], v[102:105]
	v_mfma_f32_16x16x32_bf16 v[126:129], v[162:165], v[238:241], v[126:129]
	v_mfma_f32_16x16x32_bf16 v[98:101], v[176:179], v[238:241], v[98:101]
	v_mfma_f32_16x16x32_bf16 v[122:125], v[162:165], v[246:249], v[122:125]
	v_mfma_f32_16x16x32_bf16 v[90:93], v[176:179], v[246:249], v[90:93]
	s_setprio 0
	s_setprio 1
	v_mfma_f32_16x16x32_bf16 v[82:85], v[186:189], v[208:211], v[82:85]
	v_mfma_f32_16x16x32_bf16 v[54:57], v[194:197], v[208:211], v[54:57]
	v_mfma_f32_16x16x32_bf16 v[74:77], v[186:189], v[226:229], v[74:77]
	v_mfma_f32_16x16x32_bf16 v[46:49], v[194:197], v[226:229], v[46:49]
	v_mfma_f32_16x16x32_bf16 v[66:69], v[186:189], v[234:237], v[66:69]
	v_mfma_f32_16x16x32_bf16 v[30:33], v[194:197], v[234:237], v[30:33]
	v_mfma_f32_16x16x32_bf16 v[58:61], v[186:189], v[242:245], v[58:61]
	v_mfma_f32_16x16x32_bf16 v[22:25], v[194:197], v[242:245], v[22:25]
	v_mfma_f32_16x16x32_bf16 v[82:85], v[190:193], v[218:221], v[82:85]
	v_mfma_f32_16x16x32_bf16 v[54:57], v[198:201], v[218:221], v[54:57]
	v_mfma_f32_16x16x32_bf16 v[74:77], v[190:193], v[230:233], v[74:77]
	v_mfma_f32_16x16x32_bf16 v[46:49], v[198:201], v[230:233], v[46:49]
	v_mfma_f32_16x16x32_bf16 v[66:69], v[190:193], v[238:241], v[66:69]
	v_mfma_f32_16x16x32_bf16 v[30:33], v[198:201], v[238:241], v[30:33]
	v_mfma_f32_16x16x32_bf16 v[58:61], v[190:193], v[246:249], v[58:61]
	v_mfma_f32_16x16x32_bf16 v[22:25], v[198:201], v[246:249], v[22:25]
	s_setprio 0
	s_barrier
; #define PG8_STAGE(bufoff, gbase, voff) do { _Pragma("unroll") for (int _i = 0; _i < 2; ++_i) \
;         __builtin_amdgcn_global_load_lds((const unsigned*)((const char*)(gbase) + (voff)[_i]), (PG8_LAS unsigned*)(lds + (bufoff) + ldsw + _i * 8192), 16, 0, 0); } while (0)
; #define PG8_LDA(dst, b, h) do { _Pragma("unroll") for (int m = 0; m < 4; ++m) _Pragma("unroll") for (int k = 0; k < 2; ++k) dst[m][k] = *(const PG8_LAS bf16x8*)(lds + PG8_SA(b, h) + aoff + m * 2048 + k * 1024); } while (0)
; #define PG8_MMA(ai, bj, At, Bt) do { __builtin_amdgcn_s_setprio(1); _Pragma("unroll") for (int m = 0; m < 4; ++m) _Pragma("unroll") for (int n = 0; n < 2; ++n) _Pragma("unroll") for (int k = 0; k < 2; ++k) \
;         acc[ai][bj][m][n] = __builtin_amdgcn_mfma_f32_16x16x32_bf16(Bt[n][k], At[m][k], acc[ai][bj][m][n], 0, 0, 0); __builtin_amdgcn_s_setprio(0); } while (0)
; #define PG8_WAIT_V(n) asm volatile("s_waitcnt vmcnt(" #n ")" ::: "memory")
; #define PG8_WAIT_L(n) asm volatile("s_waitcnt lgkmcnt(" #n ")" ::: "memory")
; #define PG8_BAR __builtin_amdgcn_s_barrier()
; #define PG8_SCHED __builtin_amdgcn_sched_barrier(0)
; template <class Epi, class Sched, bool ALIGN_EPI = false, bool SP2 = false>
; __device__ __forceinline__ void gemm_phase(PG8_LAS unsigned char* lds, const Gemm g, const Sched& S, const Epi& E) {
;     ...
;             PG8_LDA(At, 1, 1); PG8_STAGE(PG8_SB(1, 0), b3, voffB); PG8_STAGE(PG8_SB(1, 1), b3 + hstep, voffB); PG8_STAGE(PG8_SA(1, 0), a3, voffA);
;             PG8_WAIT_V(8); PG8_WAIT_L(0); PG8_BAR; PG8_MMA(1, 0, At, B0); PG8_MMA(1, 1, At, B1); PG8_BAR; PG8_SCHED;
	s_add_i32 s12, s43, s26
	v_lshl_add_u64 v[166:167], v[166:167], 0, s[70:71]
	s_mov_b32 m0, s12
	ds_read_b128 v[208:211], v170 offset:49152
	ds_read_b128 v[218:221], v170 offset:50176
	ds_read_b128 v[226:229], v170 offset:51200
	ds_read_b128 v[230:233], v170 offset:52224
	ds_read_b128 v[234:237], v170 offset:53248
	ds_read_b128 v[238:241], v170 offset:54272
	ds_read_b128 v[242:245], v170 offset:55296
	ds_read_b128 v[246:249], v170 offset:56320
	global_load_lds_dwordx4 v[166:167], off
	s_add_i32 m0, s12, 0x2000
	s_add_u32 s12, s16, 0xb0080
	v_lshl_add_u64 v[166:167], v[180:181], 0, s[70:71]
	s_addc_u32 s13, s17, 0
	s_add_i32 s16, s44, s26
	global_load_lds_dwordx4 v[166:167], off
	v_lshl_add_u64 v[166:167], s[12:13], 0, v[34:35]
	s_mov_b32 m0, s16
	s_nop 0
	global_load_lds_dwordx4 v[166:167], off
	v_lshl_add_u64 v[166:167], s[12:13], 0, v[36:37]
	s_add_i32 m0, s16, 0x2000
	s_nop 0
	global_load_lds_dwordx4 v[166:167], off
	v_lshl_add_u64 v[166:167], v[202:203], 0, s[70:71]
	s_mov_b32 m0, s35
	s_nop 0
	global_load_lds_dwordx4 v[166:167], off
	v_lshl_add_u64 v[166:167], v[212:213], 0, s[70:71]
	s_mov_b32 m0, s36
	s_nop 0
	global_load_lds_dwordx4 v[166:167], off
	s_waitcnt vmcnt(8)
	s_waitcnt lgkmcnt(0)
	s_barrier
	s_setprio 1
	s_waitcnt lgkmcnt(0)
	v_mfma_f32_16x16x32_bf16 v[118:121], v[138:141], v[208:211], v[118:121]
	v_mfma_f32_16x16x32_bf16 v[86:89], v[172:175], v[208:211], v[86:89]
	v_mfma_f32_16x16x32_bf16 v[114:117], v[138:141], v[226:229], v[114:117]
	v_mfma_f32_16x16x32_bf16 v[78:81], v[172:175], v[226:229], v[78:81]
	v_mfma_f32_16x16x32_bf16 v[110:113], v[138:141], v[234:237], v[110:113]
	v_mfma_f32_16x16x32_bf16 v[70:73], v[172:175], v[234:237], v[70:73]
	v_mfma_f32_16x16x32_bf16 v[94:97], v[138:141], v[242:245], v[94:97]
	v_mfma_f32_16x16x32_bf16 v[62:65], v[172:175], v[242:245], v[62:65]
	v_mfma_f32_16x16x32_bf16 v[118:121], v[162:165], v[218:221], v[118:121]
	v_mfma_f32_16x16x32_bf16 v[86:89], v[176:179], v[218:221], v[86:89]
	v_mfma_f32_16x16x32_bf16 v[114:117], v[162:165], v[230:233], v[114:117]
	v_mfma_f32_16x16x32_bf16 v[78:81], v[176:179], v[230:233], v[78:81]
	v_mfma_f32_16x16x32_bf16 v[110:113], v[162:165], v[238:241], v[110:113]
	v_mfma_f32_16x16x32_bf16 v[70:73], v[176:179], v[238:241], v[70:73]
	v_mfma_f32_16x16x32_bf16 v[94:97], v[162:165], v[246:249], v[94:97]
	v_mfma_f32_16x16x32_bf16 v[62:65], v[176:179], v[246:249], v[62:65]
	s_setprio 0
	s_setprio 1
	v_mfma_f32_16x16x32_bf16 v[50:53], v[186:189], v[208:211], v[50:53]
	v_mfma_f32_16x16x32_bf16 v[14:17], v[194:197], v[208:211], v[14:17]
	v_mfma_f32_16x16x32_bf16 v[42:45], v[186:189], v[226:229], v[42:45]
	v_mfma_f32_16x16x32_bf16 v[10:13], v[194:197], v[226:229], v[10:13]
	v_mfma_f32_16x16x32_bf16 v[26:29], v[186:189], v[234:237], v[26:29]
	v_mfma_f32_16x16x32_bf16 v[6:9], v[194:197], v[234:237], v[6:9]
	v_mfma_f32_16x16x32_bf16 v[18:21], v[186:189], v[242:245], v[18:21]
	v_mfma_f32_16x16x32_bf16 v[2:5], v[194:197], v[242:245], v[2:5]
	v_mfma_f32_16x16x32_bf16 v[50:53], v[190:193], v[218:221], v[50:53]
	v_mfma_f32_16x16x32_bf16 v[14:17], v[198:201], v[218:221], v[14:17]
	v_mfma_f32_16x16x32_bf16 v[42:45], v[190:193], v[230:233], v[42:45]
	v_mfma_f32_16x16x32_bf16 v[10:13], v[198:201], v[230:233], v[10:13]
	v_mfma_f32_16x16x32_bf16 v[26:29], v[190:193], v[238:241], v[26:29]
	v_mfma_f32_16x16x32_bf16 v[6:9], v[198:201], v[238:241], v[6:9]
	v_mfma_f32_16x16x32_bf16 v[18:21], v[190:193], v[246:249], v[18:21]
	v_mfma_f32_16x16x32_bf16 v[2:5], v[198:201], v[246:249], v[2:5]
	s_setprio 0
	s_barrier
	s_add_i32 s42, s42, 2
	s_add_u32 s11, s11, 0x100
	s_addc_u32 s41, s41, 0
	s_cmp_gt_u32 s42, 41
	s_mov_b64 s[12:13], s[14:15]
